# hyena: stage-1/stage-2 operand loads de-serialized (nx halfword loaded straight into its register, shift deferred to the commit) in both hyena layers, on top of the conv-loop rewrite
# speedup vs baseline: 1.0080x; 1.0080x over previous
.LBB0_1443:
	s_or_b64 exec, exec, s[12:13]
	v_cmp_gt_i32_e64 s[0:1], s4, v123
	s_and_saveexec_b64 s[12:13], s[0:1]
	s_cbranch_execz .LBB0_1445
	global_load_ushort v68, v[2:3], off offset:16

.LBB0_1449:
	s_or_b64 exec, exec, s[12:13]
	v_cmp_gt_i32_e64 s[0:1], s4, v78
	s_and_saveexec_b64 s[12:13], s[0:1]
	s_cbranch_execz .LBB0_1451
	global_load_ushort v66, v[2:3], off offset:16

.LBB0_1455:
	s_or_b64 exec, exec, s[26:27]
	v_cmp_gt_i32_e64 s[0:1], s4, v94
	s_and_saveexec_b64 s[26:27], s[0:1]
	s_cbranch_execz .LBB0_1457
	global_load_ushort v64, v[2:3], off offset:16

.LBB0_1461:
	s_or_b64 exec, exec, s[28:29]
	v_cmp_gt_i32_e64 s[0:1], s4, v95
	s_and_saveexec_b64 s[28:29], s[0:1]
	s_cbranch_execz .LBB0_1463
	global_load_ushort v62, v[2:3], off offset:16

.LBB0_1467:
	s_or_b64 exec, exec, s[30:31]
	v_cmp_gt_i32_e64 s[0:1], s4, v123
	s_and_saveexec_b64 s[30:31], s[0:1]
	s_cbranch_execz .LBB0_1469
	global_load_ushort v60, v[2:3], off offset:16

.LBB0_1473:
	s_or_b64 exec, exec, s[30:31]
	v_cmp_gt_i32_e64 s[0:1], s4, v78
	s_and_saveexec_b64 s[30:31], s[0:1]
	s_cbranch_execz .LBB0_1475
	global_load_ushort v58, v[2:3], off offset:16

.LBB0_1479:
	s_or_b64 exec, exec, s[30:31]
	v_cmp_gt_i32_e64 s[0:1], s4, v94
	s_and_saveexec_b64 s[30:31], s[0:1]
	s_cbranch_execz .LBB0_1481
	global_load_ushort v56, v[2:3], off offset:16

.LBB0_1485:
	s_or_b64 exec, exec, s[30:31]
	v_cmp_gt_i32_e64 s[0:1], s4, v95
	s_and_saveexec_b64 s[30:31], s[0:1]
	s_cbranch_execz .LBB0_1487
	global_load_ushort v54, v[70:71], off offset:16
.LBB0_1487:
	s_or_b64 exec, exec, s[30:31]
	s_or_b64 exec, exec, s[28:29]
	v_lshl_add_u32 v125, v139, 4, 0
	s_and_saveexec_b64 s[0:1], s[6:7]
	s_cbranch_execnz .LBB0_1503

.LBB0_1490:
	s_or_b64 exec, exec, s[0:1]
	v_readlane_b32 s48, v250, 41
	s_lshl_b64 s[0:1], s[20:21], 2
	v_readlane_b32 s58, v250, 51
	v_readlane_b32 s59, v250, 52
	s_add_u32 s30, s58, s0
	v_readlane_b32 s60, v250, 53
	s_addc_u32 s31, s59, s1
	v_readlane_b32 s61, v250, 54
	s_add_u32 s34, s60, s0
	s_addc_u32 s35, s61, s1
	global_load_dword v140, v115, s[30:31]
	global_load_dword v119, v130, s[30:31]
	global_load_dword v141, v115, s[34:35]
	global_load_dword v118, v131, s[30:31]
	v_ashrrev_i32_e32 v22, 31, v139
	v_add_u32_sdwa v129, v139, v22 dst_sel:DWORD dst_unused:UNUSED_PAD src0_sel:DWORD src1_sel:BYTE_3
	v_readlane_b32 s49, v250, 42
	v_readlane_b32 s50, v250, 43
	v_readlane_b32 s51, v250, 44
	v_readlane_b32 s52, v250, 45
	v_readlane_b32 s53, v250, 46
	v_readlane_b32 s54, v250, 47
	v_readlane_b32 s55, v250, 48
	v_readlane_b32 s56, v250, 49
	v_readlane_b32 s57, v250, 50
	v_readlane_b32 s62, v250, 55
	v_readlane_b32 s63, v250, 56
	s_and_saveexec_b64 s[0:1], vcc
	s_cbranch_execz .LBB0_1492
	v_lshlrev_b32_e32 v22, 16, v67
	s_waitcnt vmcnt(1)
	v_fma_f32 v41, v140, v22, v141
	v_and_b32_e32 v22, 0xffff0000, v36
	v_lshlrev_b32_e32 v25, 16, v36
	v_mov_b32_e32 v24, v22
	s_waitcnt vmcnt(0)
	v_pk_mul_f32 v[30:31], v[118:119], v[24:25]
	v_and_b32_e32 v23, 16, v36
	v_add_f32_e32 v24, v31, v41
	v_add_f32_e32 v36, v30, v24
	v_and_b32_e32 v24, 0xffff0000, v37
	v_lshlrev_b32_e32 v31, 16, v37
	v_mov_b32_e32 v30, v24
	v_fma_f32 v42, v140, v22, v141
	v_pk_mov_b32 v[22:23], v[30:31], v[22:23] op_sel:[1,0]
	v_fma_f32 v41, v140, v25, v141
	v_pk_mul_f32 v[22:23], v[118:119], v[22:23]
	v_and_b32_e32 v25, 16, v37
	v_add_f32_e32 v23, v23, v41
	v_add_f32_e32 v37, v22, v23
	v_pk_mul_f32 v[22:23], v[118:119], v[30:31]
	v_fma_f32 v43, v140, v24, v141
	v_add_f32_e32 v23, v23, v42
	v_add_f32_e32 v41, v22, v23
	v_and_b32_e32 v22, 0xffff0000, v38
	v_fma_f32 v42, v140, v31, v141
	v_lshlrev_b32_e32 v31, 16, v38
	v_mov_b32_e32 v30, v22
	v_pk_mov_b32 v[24:25], v[30:31], v[24:25] op_sel:[1,0]
	v_and_b32_e32 v23, 16, v38
	v_pk_mul_f32 v[24:25], v[118:119], v[24:25]
	v_lshrrev_b32_e32 v40, 8, v129
	v_add_f32_e32 v25, v25, v42
	v_add_f32_e32 v38, v24, v25
	v_pk_mul_f32 v[24:25], v[118:119], v[30:31]
	v_fma_f32 v42, v140, v22, v141
	v_add_f32_e32 v25, v25, v43
	v_add_f32_e32 v30, v24, v25
	v_and_b32_e32 v24, 0xffff0000, v39
	v_lshlrev_b32_e32 v25, 16, v39
	v_pk_mov_b32 v[22:23], v[24:25], v[22:23] op_sel:[1,0]
	v_fma_f32 v31, v140, v31, v141
	v_pk_mul_f32 v[22:23], v[118:119], v[22:23]
	v_mov_b32_e32 v69, v24
	v_add_f32_e32 v23, v23, v31
	v_add_f32_e32 v31, v22, v23
	v_pk_mul_f32 v[22:23], v[118:119], v[24:25]
	v_fma_f32 v25, v140, v25, v141
	v_add_f32_e32 v23, v23, v42
	v_add_f32_e32 v39, v22, v23
	s_waitcnt vmcnt(0)
	v_lshlrev_b32_e32 v68, 16, v68
	v_pk_mul_f32 v[22:23], v[68:69], v[118:119]
	s_nop 0
	v_add_f32_e32 v23, v23, v25
	v_add_f32_e32 v25, v22, v23
	v_cvt_pk_bf16_f32 v22, v36, v37
	v_cvt_pk_bf16_f32 v23, v41, v38
	v_cvt_pk_bf16_f32 v24, v30, v31
	v_mad_i32_i24 v30, v40, s70, v123
	v_lshl_add_u32 v30, v30, 1, 0
	v_cvt_pk_bf16_f32 v25, v39, v25
	ds_write_b128 v30, v[22:25] offset:33920
.LBB0_1492:
	s_or_b64 exec, exec, s[0:1]
	v_add_u32_e32 v127, 0x200, v139
	v_lshlrev_b32_e32 v144, 3, v127
	v_bfe_i32 v150, v127, 28, 1
	v_ashrrev_i32_e32 v146, 31, v127
	s_and_saveexec_b64 s[0:1], s[14:15]
	s_cbranch_execz .LBB0_1494
	v_lshrrev_b32_e32 v22, 21, v150
	v_add_u32_e32 v22, v144, v22
	v_and_b32_e32 v22, 0x7ffff800, v22
	v_sub_u32_e32 v36, v144, v22
	v_add_u32_sdwa v22, v127, v146 dst_sel:DWORD dst_unused:UNUSED_PAD src0_sel:DWORD src1_sel:BYTE_3
	v_lshrrev_b32_e32 v37, 8, v22
	s_waitcnt vmcnt(4)
	v_lshlrev_b32_e32 v22, 16, v65
	s_waitcnt vmcnt(1)
	v_fma_f32 v38, v140, v22, v141
	v_and_b32_e32 v22, 0xffff0000, v32
	v_lshlrev_b32_e32 v25, 16, v32
	v_mov_b32_e32 v24, v22
	s_waitcnt vmcnt(0)
	v_pk_mul_f32 v[30:31], v[118:119], v[24:25]
	v_and_b32_e32 v23, 16, v32
	v_add_f32_e32 v24, v31, v38
	v_add_f32_e32 v32, v30, v24
	v_and_b32_e32 v24, 0xffff0000, v33
	v_lshlrev_b32_e32 v31, 16, v33
	v_mov_b32_e32 v30, v24
	v_fma_f32 v39, v140, v22, v141
	v_pk_mov_b32 v[22:23], v[30:31], v[22:23] op_sel:[1,0]
	v_fma_f32 v38, v140, v25, v141
	v_pk_mul_f32 v[22:23], v[118:119], v[22:23]
	v_and_b32_e32 v25, 16, v33
	v_add_f32_e32 v23, v23, v38
	v_add_f32_e32 v33, v22, v23
	v_pk_mul_f32 v[22:23], v[118:119], v[30:31]
	v_fma_f32 v40, v140, v24, v141
	v_add_f32_e32 v23, v23, v39
	v_add_f32_e32 v38, v22, v23
	v_and_b32_e32 v22, 0xffff0000, v34
	v_fma_f32 v39, v140, v31, v141
	v_lshlrev_b32_e32 v31, 16, v34
	v_mov_b32_e32 v30, v22
	v_pk_mov_b32 v[24:25], v[30:31], v[24:25] op_sel:[1,0]
	v_and_b32_e32 v23, 16, v34
	v_pk_mul_f32 v[24:25], v[118:119], v[24:25]
	s_nop 0
	v_add_f32_e32 v25, v25, v39
	v_add_f32_e32 v34, v24, v25
	v_pk_mul_f32 v[24:25], v[118:119], v[30:31]
	v_fma_f32 v39, v140, v22, v141
	v_add_f32_e32 v25, v25, v40
	v_add_f32_e32 v30, v24, v25
	v_and_b32_e32 v24, 0xffff0000, v35
	v_lshlrev_b32_e32 v25, 16, v35
	v_pk_mov_b32 v[22:23], v[24:25], v[22:23] op_sel:[1,0]
	v_fma_f32 v31, v140, v31, v141
	v_pk_mul_f32 v[22:23], v[118:119], v[22:23]
	v_mov_b32_e32 v67, v24
	v_add_f32_e32 v23, v23, v31
	v_add_f32_e32 v31, v22, v23
	v_pk_mul_f32 v[22:23], v[118:119], v[24:25]
	v_fma_f32 v25, v140, v25, v141
	v_add_f32_e32 v23, v23, v39
	v_add_f32_e32 v35, v22, v23
	s_waitcnt vmcnt(0)
	v_lshlrev_b32_e32 v66, 16, v66
	v_pk_mul_f32 v[22:23], v[66:67], v[118:119]
	s_nop 0
	v_add_f32_e32 v23, v23, v25
	v_add_f32_e32 v25, v22, v23
	v_cvt_pk_bf16_f32 v22, v32, v33
	v_cvt_pk_bf16_f32 v23, v38, v34
	v_cvt_pk_bf16_f32 v24, v30, v31
	v_mad_i32_i24 v30, v37, s70, v36
	v_lshl_add_u32 v30, v30, 1, 0
	v_cvt_pk_bf16_f32 v25, v35, v25
	ds_write_b128 v30, v[22:25] offset:33920
.LBB0_1494:
	s_or_b64 exec, exec, s[0:1]
	v_add_u32_e32 v145, 0x400, v139
	v_lshlrev_b32_e32 v147, 3, v145
	v_bfe_i32 v153, v145, 28, 1
	v_ashrrev_i32_e32 v149, 31, v145
	s_and_saveexec_b64 s[0:1], s[12:13]
	s_cbranch_execz .LBB0_1496
	v_lshrrev_b32_e32 v22, 21, v153
	v_add_u32_e32 v22, v147, v22
	v_and_b32_e32 v22, 0x7ffff800, v22
	s_waitcnt vmcnt(4)
	v_sub_u32_e32 v32, v147, v22
	v_add_u32_sdwa v22, v145, v149 dst_sel:DWORD dst_unused:UNUSED_PAD src0_sel:DWORD src1_sel:BYTE_3
	v_lshrrev_b32_e32 v33, 8, v22
	v_lshlrev_b32_e32 v22, 16, v63
	s_waitcnt vmcnt(1)
	v_fma_f32 v34, v140, v22, v141
	v_and_b32_e32 v22, 0xffff0000, v26
	v_lshlrev_b32_e32 v25, 16, v26
	v_mov_b32_e32 v24, v22
	s_waitcnt vmcnt(0)
	v_pk_mul_f32 v[30:31], v[118:119], v[24:25]
	v_and_b32_e32 v23, 16, v26
	v_add_f32_e32 v24, v31, v34
	v_add_f32_e32 v30, v30, v24
	v_and_b32_e32 v24, 0xffff0000, v27
	v_fma_f32 v31, v140, v25, v141
	v_and_b32_e32 v25, 16, v27
	v_lshlrev_b32_e32 v27, 16, v27
	v_mov_b32_e32 v26, v24
	v_fma_f32 v34, v140, v22, v141
	v_pk_mov_b32 v[22:23], v[26:27], v[22:23] op_sel:[1,0]
	v_fma_f32 v35, v140, v27, v141
	v_pk_mul_f32 v[22:23], v[118:119], v[22:23]
	v_fma_f32 v36, v140, v24, v141
	v_add_f32_e32 v23, v23, v31
	v_add_f32_e32 v31, v22, v23
	v_pk_mul_f32 v[22:23], v[118:119], v[26:27]
	v_lshlrev_b32_e32 v27, 16, v28
	v_add_f32_e32 v23, v23, v34
	v_add_f32_e32 v34, v22, v23
	v_and_b32_e32 v22, 0xffff0000, v28
	v_mov_b32_e32 v26, v22
	v_pk_mov_b32 v[24:25], v[26:27], v[24:25] op_sel:[1,0]
	v_and_b32_e32 v23, 16, v28
	v_pk_mul_f32 v[24:25], v[118:119], v[24:25]
	s_nop 0
	v_add_f32_e32 v25, v25, v35
	v_add_f32_e32 v28, v24, v25
	v_pk_mul_f32 v[24:25], v[118:119], v[26:27]
	v_fma_f32 v35, v140, v22, v141
	v_add_f32_e32 v25, v25, v36
	v_add_f32_e32 v26, v24, v25
	v_and_b32_e32 v24, 0xffff0000, v29
	v_lshlrev_b32_e32 v25, 16, v29
	v_pk_mov_b32 v[22:23], v[24:25], v[22:23] op_sel:[1,0]
	v_fma_f32 v27, v140, v27, v141
	v_pk_mul_f32 v[22:23], v[118:119], v[22:23]
	v_mov_b32_e32 v65, v24
	v_add_f32_e32 v23, v23, v27
	v_add_f32_e32 v27, v22, v23
	v_pk_mul_f32 v[22:23], v[118:119], v[24:25]
	v_fma_f32 v25, v140, v25, v141
	v_add_f32_e32 v23, v23, v35
	v_add_f32_e32 v29, v22, v23
	s_waitcnt vmcnt(0)
	v_lshlrev_b32_e32 v64, 16, v64
	v_pk_mul_f32 v[22:23], v[64:65], v[118:119]
	s_nop 0
	v_add_f32_e32 v23, v23, v25
	v_add_f32_e32 v25, v22, v23
	v_cvt_pk_bf16_f32 v22, v30, v31
	v_cvt_pk_bf16_f32 v23, v34, v28
	v_cvt_pk_bf16_f32 v24, v26, v27
	v_mad_i32_i24 v26, v33, s70, v32
	v_lshl_add_u32 v26, v26, 1, 0
	v_cvt_pk_bf16_f32 v25, v29, v25
	ds_write_b128 v26, v[22:25] offset:33920
.LBB0_1496:
	s_or_b64 exec, exec, s[0:1]
	v_add_u32_e32 v148, 0x600, v139
	v_lshlrev_b32_e32 v151, 3, v148
	v_bfe_i32 v154, v148, 28, 1
	v_ashrrev_i32_e32 v152, 31, v148
	s_and_saveexec_b64 s[0:1], s[10:11]
	s_cbranch_execz .LBB0_1498
	v_lshrrev_b32_e32 v22, 21, v154
	v_add_u32_e32 v22, v151, v22
	v_and_b32_e32 v22, 0x7ffff800, v22
	s_waitcnt vmcnt(4)
	v_sub_u32_e32 v28, v151, v22
	v_add_u32_sdwa v22, v148, v152 dst_sel:DWORD dst_unused:UNUSED_PAD src0_sel:DWORD src1_sel:BYTE_3
	v_lshrrev_b32_e32 v29, 8, v22
	v_lshlrev_b32_e32 v22, 16, v61
	s_waitcnt vmcnt(1)
	v_fma_f32 v30, v140, v22, v141
	v_and_b32_e32 v22, 0xffff0000, v18
	v_lshlrev_b32_e32 v25, 16, v18
	v_mov_b32_e32 v24, v22
	s_waitcnt vmcnt(0)
	v_pk_mul_f32 v[26:27], v[118:119], v[24:25]
	v_and_b32_e32 v23, 16, v18
	v_add_f32_e32 v18, v27, v30
	v_and_b32_e32 v24, 0xffff0000, v19
	v_add_f32_e32 v26, v26, v18
	v_fma_f32 v27, v140, v25, v141
	v_and_b32_e32 v25, 16, v19
	v_lshlrev_b32_e32 v19, 16, v19
	v_mov_b32_e32 v18, v24
	v_fma_f32 v30, v140, v22, v141
	v_pk_mov_b32 v[22:23], v[18:19], v[22:23] op_sel:[1,0]
	v_fma_f32 v32, v140, v24, v141
	v_pk_mul_f32 v[22:23], v[118:119], v[22:23]
	v_fma_f32 v31, v140, v19, v141
	v_add_f32_e32 v23, v23, v27
	v_add_f32_e32 v27, v22, v23
	v_pk_mul_f32 v[22:23], v[118:119], v[18:19]
	v_and_b32_e32 v19, 16, v20
	v_add_f32_e32 v18, v23, v30
	v_add_f32_e32 v30, v22, v18
	v_and_b32_e32 v18, 0xffff0000, v20
	v_lshlrev_b32_e32 v23, 16, v20
	v_mov_b32_e32 v22, v18
	v_pk_mov_b32 v[24:25], v[22:23], v[24:25] op_sel:[1,0]
	s_nop 0
	v_pk_mul_f32 v[24:25], v[118:119], v[24:25]
	s_nop 0
	v_add_f32_e32 v20, v25, v31
	v_add_f32_e32 v31, v24, v20
	v_pk_mul_f32 v[24:25], v[118:119], v[22:23]
	v_fma_f32 v23, v140, v23, v141
	v_add_f32_e32 v20, v25, v32
	v_add_f32_e32 v22, v24, v20
	v_and_b32_e32 v20, 0xffff0000, v21
	v_lshlrev_b32_e32 v21, 16, v21
	v_fma_f32 v24, v140, v18, v141
	v_pk_mov_b32 v[18:19], v[20:21], v[18:19] op_sel:[1,0]
	v_mov_b32_e32 v63, v20
	v_pk_mul_f32 v[18:19], v[118:119], v[18:19]
	s_nop 0
	v_add_f32_e32 v19, v19, v23
	v_add_f32_e32 v23, v18, v19
	v_pk_mul_f32 v[18:19], v[118:119], v[20:21]
	v_fma_f32 v21, v140, v21, v141
	v_add_f32_e32 v19, v19, v24
	v_add_f32_e32 v24, v18, v19
	s_waitcnt vmcnt(0)
	v_lshlrev_b32_e32 v62, 16, v62
	v_pk_mul_f32 v[18:19], v[62:63], v[118:119]
	s_nop 0
	v_add_f32_e32 v19, v19, v21
	v_add_f32_e32 v21, v18, v19
	v_cvt_pk_bf16_f32 v18, v26, v27
	v_cvt_pk_bf16_f32 v19, v30, v31
	v_cvt_pk_bf16_f32 v20, v22, v23
	v_mad_i32_i24 v22, v29, s70, v28
	v_lshl_add_u32 v22, v22, 1, 0
	v_cvt_pk_bf16_f32 v21, v24, v21
	ds_write_b128 v22, v[18:21] offset:33920
.LBB0_1498:
	s_or_b64 exec, exec, s[0:1]
	global_load_dword v121, v133, s[30:31]
	global_load_dword v120, v134, s[30:31]
	global_load_dword v143, v132, s[30:31]
	global_load_dword v142, v132, s[34:35]
	s_and_saveexec_b64 s[0:1], vcc
	s_cbranch_execz .LBB0_1504
	s_waitcnt vmcnt(8)
	v_lshlrev_b32_e32 v18, 16, v59
	s_waitcnt vmcnt(0)
	v_fma_f32 v25, v143, v18, v142
	v_and_b32_e32 v18, 0xffff0000, v14
	v_lshlrev_b32_e32 v21, 16, v14
	v_mov_b32_e32 v20, v18
	v_pk_mul_f32 v[22:23], v[120:121], v[20:21]
	v_and_b32_e32 v19, 16, v14
	v_add_f32_e32 v14, v23, v25
	v_and_b32_e32 v20, 0xffff0000, v15
	v_add_f32_e32 v22, v22, v14
	v_fma_f32 v23, v143, v21, v142
	v_and_b32_e32 v21, 16, v15
	v_lshlrev_b32_e32 v15, 16, v15
	v_mov_b32_e32 v14, v20
	v_fma_f32 v25, v143, v18, v142
	v_pk_mov_b32 v[18:19], v[14:15], v[18:19] op_sel:[1,0]
	v_fma_f32 v27, v143, v20, v142
	v_pk_mul_f32 v[18:19], v[120:121], v[18:19]
	v_fma_f32 v26, v143, v15, v142
	v_add_f32_e32 v19, v19, v23
	v_add_f32_e32 v23, v18, v19
	v_pk_mul_f32 v[18:19], v[120:121], v[14:15]
	v_and_b32_e32 v15, 16, v16
	v_add_f32_e32 v14, v19, v25
	v_add_f32_e32 v25, v18, v14
	v_and_b32_e32 v14, 0xffff0000, v16
	v_lshlrev_b32_e32 v19, 16, v16
	v_mov_b32_e32 v18, v14
	v_pk_mov_b32 v[20:21], v[18:19], v[20:21] op_sel:[1,0]
	v_lshrrev_b32_e32 v24, 8, v129
	v_pk_mul_f32 v[20:21], v[120:121], v[20:21]
	s_nop 0
	v_add_f32_e32 v16, v21, v26
	v_add_f32_e32 v26, v20, v16
	v_pk_mul_f32 v[20:21], v[120:121], v[18:19]
	v_fma_f32 v19, v143, v19, v142
	v_add_f32_e32 v16, v21, v27
	v_add_f32_e32 v18, v20, v16
	v_and_b32_e32 v16, 0xffff0000, v17
	v_lshlrev_b32_e32 v17, 16, v17
	v_fma_f32 v20, v143, v14, v142
	v_pk_mov_b32 v[14:15], v[16:17], v[14:15] op_sel:[1,0]
	v_mov_b32_e32 v61, v16
	v_pk_mul_f32 v[14:15], v[120:121], v[14:15]
	s_nop 0
	v_add_f32_e32 v15, v15, v19
	v_add_f32_e32 v19, v14, v15
	v_pk_mul_f32 v[14:15], v[120:121], v[16:17]
	v_fma_f32 v17, v143, v17, v142
	v_add_f32_e32 v15, v15, v20
	v_add_f32_e32 v20, v14, v15
	s_waitcnt vmcnt(0)
	v_lshlrev_b32_e32 v60, 16, v60
	v_pk_mul_f32 v[14:15], v[60:61], v[120:121]
	s_nop 0
	v_add_f32_e32 v15, v15, v17
	v_add_f32_e32 v17, v14, v15
	v_cvt_pk_bf16_f32 v14, v22, v23
	v_cvt_pk_bf16_f32 v15, v25, v26
	v_cvt_pk_bf16_f32 v16, v18, v19
	v_mad_i32_i24 v18, v24, s71, v123
	v_lshl_add_u32 v18, v18, 1, 0
	v_add_u32_e32 v18, 0x14100, v18
	v_cvt_pk_bf16_f32 v17, v20, v17
	ds_write_b128 v18, v[14:17]
	s_or_b64 exec, exec, s[0:1]
	s_and_saveexec_b64 s[0:1], s[14:15]
	s_cbranch_execnz .LBB0_1505

.LBB0_1501:
	s_waitcnt vmcnt(8)
	v_lshrrev_b32_e32 v10, 21, v153
	v_add_u32_e32 v10, v147, v10
	v_and_b32_e32 v10, 0x7ffff800, v10
	v_sub_u32_e32 v16, v147, v10
	v_add_u32_sdwa v10, v145, v149 dst_sel:DWORD dst_unused:UNUSED_PAD src0_sel:DWORD src1_sel:BYTE_3
	v_lshrrev_b32_e32 v17, 8, v10
	v_lshlrev_b32_e32 v10, 16, v55
	s_waitcnt vmcnt(0)
	v_fma_f32 v18, v143, v10, v142
	v_and_b32_e32 v10, 0xffff0000, v6
	v_lshlrev_b32_e32 v13, 16, v6
	v_mov_b32_e32 v12, v10
	v_pk_mul_f32 v[14:15], v[120:121], v[12:13]
	v_and_b32_e32 v11, 16, v6
	v_add_f32_e32 v6, v15, v18
	v_and_b32_e32 v12, 0xffff0000, v7
	v_add_f32_e32 v14, v14, v6
	v_fma_f32 v15, v143, v13, v142
	v_and_b32_e32 v13, 16, v7
	v_lshlrev_b32_e32 v7, 16, v7
	v_mov_b32_e32 v6, v12
	v_fma_f32 v18, v143, v10, v142
	v_pk_mov_b32 v[10:11], v[6:7], v[10:11] op_sel:[1,0]
	v_fma_f32 v20, v143, v12, v142
	v_pk_mul_f32 v[10:11], v[120:121], v[10:11]
	v_fma_f32 v19, v143, v7, v142
	v_add_f32_e32 v11, v11, v15
	v_add_f32_e32 v15, v10, v11
	v_pk_mul_f32 v[10:11], v[120:121], v[6:7]
	v_and_b32_e32 v7, 16, v8
	v_add_f32_e32 v6, v11, v18
	v_add_f32_e32 v18, v10, v6
	v_and_b32_e32 v6, 0xffff0000, v8
	v_lshlrev_b32_e32 v11, 16, v8
	v_mov_b32_e32 v10, v6
	v_pk_mov_b32 v[12:13], v[10:11], v[12:13] op_sel:[1,0]
	s_nop 0
	v_pk_mul_f32 v[12:13], v[120:121], v[12:13]
	s_nop 0
	v_add_f32_e32 v8, v13, v19
	v_add_f32_e32 v19, v12, v8
	v_pk_mul_f32 v[12:13], v[120:121], v[10:11]
	v_fma_f32 v11, v143, v11, v142
	v_add_f32_e32 v8, v13, v20
	v_add_f32_e32 v10, v12, v8
	v_and_b32_e32 v8, 0xffff0000, v9
	v_lshlrev_b32_e32 v9, 16, v9
	v_fma_f32 v12, v143, v6, v142
	v_pk_mov_b32 v[6:7], v[8:9], v[6:7] op_sel:[1,0]
	v_mov_b32_e32 v57, v8
	v_pk_mul_f32 v[6:7], v[120:121], v[6:7]
	s_nop 0
	v_add_f32_e32 v7, v7, v11
	v_add_f32_e32 v11, v6, v7
	v_pk_mul_f32 v[6:7], v[120:121], v[8:9]
	v_fma_f32 v9, v143, v9, v142
	v_add_f32_e32 v7, v7, v12
	v_add_f32_e32 v12, v6, v7
	s_waitcnt vmcnt(0)
	v_lshlrev_b32_e32 v56, 16, v56
	v_pk_mul_f32 v[6:7], v[56:57], v[120:121]
	s_nop 0
	v_add_f32_e32 v7, v7, v9
	v_add_f32_e32 v9, v6, v7
	v_cvt_pk_bf16_f32 v6, v14, v15
	v_cvt_pk_bf16_f32 v7, v18, v19
	v_cvt_pk_bf16_f32 v8, v10, v11
	v_mad_i32_i24 v10, v17, s71, v16
	v_lshl_add_u32 v10, v10, 1, 0
	v_add_u32_e32 v10, 0x14100, v10
	v_cvt_pk_bf16_f32 v9, v12, v9
	ds_write_b128 v10, v[6:9]
	s_or_b64 exec, exec, s[0:1]
	s_and_saveexec_b64 s[0:1], s[10:11]
	s_cbranch_execnz .LBB0_1507
	s_branch .LBB0_1508

.LBB0_1505:
	s_waitcnt vmcnt(8)
	v_lshrrev_b32_e32 v14, 21, v150
	v_add_u32_e32 v14, v144, v14
	v_and_b32_e32 v14, 0x7ffff800, v14
	v_sub_u32_e32 v20, v144, v14
	v_add_u32_sdwa v14, v127, v146 dst_sel:DWORD dst_unused:UNUSED_PAD src0_sel:DWORD src1_sel:BYTE_3
	v_lshrrev_b32_e32 v21, 8, v14
	v_lshlrev_b32_e32 v14, 16, v57
	s_waitcnt vmcnt(0)
	v_fma_f32 v22, v143, v14, v142
	v_and_b32_e32 v14, 0xffff0000, v10
	v_lshlrev_b32_e32 v17, 16, v10
	v_mov_b32_e32 v16, v14
	v_pk_mul_f32 v[18:19], v[120:121], v[16:17]
	v_and_b32_e32 v15, 16, v10
	v_add_f32_e32 v10, v19, v22
	v_and_b32_e32 v16, 0xffff0000, v11
	v_add_f32_e32 v18, v18, v10
	v_fma_f32 v19, v143, v17, v142
	v_and_b32_e32 v17, 16, v11
	v_lshlrev_b32_e32 v11, 16, v11
	v_mov_b32_e32 v10, v16
	v_fma_f32 v22, v143, v14, v142
	v_pk_mov_b32 v[14:15], v[10:11], v[14:15] op_sel:[1,0]
	v_fma_f32 v24, v143, v16, v142
	v_pk_mul_f32 v[14:15], v[120:121], v[14:15]
	v_fma_f32 v23, v143, v11, v142
	v_add_f32_e32 v15, v15, v19
	v_add_f32_e32 v19, v14, v15
	v_pk_mul_f32 v[14:15], v[120:121], v[10:11]
	v_and_b32_e32 v11, 16, v12
	v_add_f32_e32 v10, v15, v22
	v_add_f32_e32 v22, v14, v10
	v_and_b32_e32 v10, 0xffff0000, v12
	v_lshlrev_b32_e32 v15, 16, v12
	v_mov_b32_e32 v14, v10
	v_pk_mov_b32 v[16:17], v[14:15], v[16:17] op_sel:[1,0]
	s_nop 0
	v_pk_mul_f32 v[16:17], v[120:121], v[16:17]
	s_nop 0
	v_add_f32_e32 v12, v17, v23
	v_add_f32_e32 v23, v16, v12
	v_pk_mul_f32 v[16:17], v[120:121], v[14:15]
	v_fma_f32 v15, v143, v15, v142
	v_add_f32_e32 v12, v17, v24
	v_add_f32_e32 v14, v16, v12
	v_and_b32_e32 v12, 0xffff0000, v13
	v_lshlrev_b32_e32 v13, 16, v13
	v_fma_f32 v16, v143, v10, v142
	v_pk_mov_b32 v[10:11], v[12:13], v[10:11] op_sel:[1,0]
	v_mov_b32_e32 v59, v12
	v_pk_mul_f32 v[10:11], v[120:121], v[10:11]
	s_nop 0
	v_add_f32_e32 v11, v11, v15
	v_add_f32_e32 v15, v10, v11
	v_pk_mul_f32 v[10:11], v[120:121], v[12:13]
	v_fma_f32 v13, v143, v13, v142
	v_add_f32_e32 v11, v11, v16
	v_add_f32_e32 v16, v10, v11
	s_waitcnt vmcnt(0)
	v_lshlrev_b32_e32 v58, 16, v58
	v_pk_mul_f32 v[10:11], v[58:59], v[120:121]
	s_nop 0
	v_add_f32_e32 v11, v11, v13
	v_add_f32_e32 v13, v10, v11
	v_cvt_pk_bf16_f32 v10, v18, v19
	v_cvt_pk_bf16_f32 v11, v22, v23
	v_cvt_pk_bf16_f32 v12, v14, v15
	v_mad_i32_i24 v14, v21, s71, v20
	v_lshl_add_u32 v14, v14, 1, 0
	v_add_u32_e32 v14, 0x14100, v14
	v_cvt_pk_bf16_f32 v13, v16, v13
	ds_write_b128 v14, v[10:13]
	s_or_b64 exec, exec, s[0:1]
	s_and_saveexec_b64 s[0:1], s[12:13]
	s_cbranch_execnz .LBB0_1501

.LBB0_1507:
	s_waitcnt vmcnt(8)
	v_lshrrev_b32_e32 v6, 21, v154
	v_add_u32_e32 v6, v151, v6
	v_and_b32_e32 v6, 0x7ffff800, v6
	v_sub_u32_e32 v12, v151, v6
	v_add_u32_sdwa v6, v148, v152 dst_sel:DWORD dst_unused:UNUSED_PAD src0_sel:DWORD src1_sel:BYTE_3
	v_lshrrev_b32_e32 v13, 8, v6
	v_lshlrev_b32_e32 v6, 16, v49
	s_waitcnt vmcnt(0)
	v_fma_f32 v14, v143, v6, v142
	v_and_b32_e32 v6, 0xffff0000, v2
	v_lshlrev_b32_e32 v9, 16, v2
	v_mov_b32_e32 v8, v6
	v_pk_mul_f32 v[10:11], v[120:121], v[8:9]
	v_and_b32_e32 v7, 16, v2
	v_add_f32_e32 v2, v11, v14
	v_and_b32_e32 v8, 0xffff0000, v3
	v_add_f32_e32 v10, v10, v2
	v_fma_f32 v11, v143, v9, v142
	v_and_b32_e32 v9, 16, v3
	v_lshlrev_b32_e32 v3, 16, v3
	v_mov_b32_e32 v2, v8
	v_fma_f32 v14, v143, v6, v142
	v_pk_mov_b32 v[6:7], v[2:3], v[6:7] op_sel:[1,0]
	v_fma_f32 v16, v143, v8, v142
	v_pk_mul_f32 v[6:7], v[120:121], v[6:7]
	v_fma_f32 v15, v143, v3, v142
	v_add_f32_e32 v7, v7, v11
	v_add_f32_e32 v11, v6, v7
	v_pk_mul_f32 v[6:7], v[120:121], v[2:3]
	v_and_b32_e32 v3, 16, v4
	v_add_f32_e32 v2, v7, v14
	v_add_f32_e32 v14, v6, v2
	v_and_b32_e32 v2, 0xffff0000, v4
	v_lshlrev_b32_e32 v7, 16, v4
	v_mov_b32_e32 v6, v2
	v_pk_mov_b32 v[8:9], v[6:7], v[8:9] op_sel:[1,0]
	s_nop 0
	v_pk_mul_f32 v[8:9], v[120:121], v[8:9]
	s_nop 0
	v_add_f32_e32 v4, v9, v15
	v_add_f32_e32 v15, v8, v4
	v_pk_mul_f32 v[8:9], v[120:121], v[6:7]
	v_fma_f32 v7, v143, v7, v142
	v_add_f32_e32 v4, v9, v16
	v_add_f32_e32 v6, v8, v4
	v_and_b32_e32 v4, 0xffff0000, v5
	v_lshlrev_b32_e32 v5, 16, v5
	v_fma_f32 v8, v143, v2, v142
	v_pk_mov_b32 v[2:3], v[4:5], v[2:3] op_sel:[1,0]
	v_mov_b32_e32 v55, v4
	v_pk_mul_f32 v[2:3], v[120:121], v[2:3]
	s_nop 0
	v_add_f32_e32 v3, v3, v7
	v_add_f32_e32 v7, v2, v3
	v_pk_mul_f32 v[2:3], v[120:121], v[4:5]
	v_fma_f32 v5, v143, v5, v142
	v_add_f32_e32 v3, v3, v8
	v_add_f32_e32 v8, v2, v3
	s_waitcnt vmcnt(0)
	v_lshlrev_b32_e32 v54, 16, v54
	v_pk_mul_f32 v[2:3], v[54:55], v[120:121]
	s_nop 0
	v_add_f32_e32 v3, v3, v5
	v_add_f32_e32 v5, v2, v3
	v_cvt_pk_bf16_f32 v2, v10, v11
	v_cvt_pk_bf16_f32 v3, v14, v15
	v_cvt_pk_bf16_f32 v4, v6, v7
	v_mad_i32_i24 v6, v13, s71, v12
	v_lshl_add_u32 v6, v6, 1, 0
	v_add_u32_e32 v6, 0x14100, v6
	v_cvt_pk_bf16_f32 v5, v8, v5
	ds_write_b128 v6, v[2:5]

.LBB0_1523:
	s_or_b64 exec, exec, s[36:37]
	v_cmp_gt_i32_e64 s[0:1], s4, v123
	s_and_saveexec_b64 s[36:37], s[0:1]
	s_cbranch_execz .LBB0_1525
	global_load_ushort v128, v[2:3], off offset:16

.LBB0_1529:
	s_or_b64 exec, exec, s[36:37]
	v_cmp_gt_i32_e64 s[0:1], s4, v78
	s_and_saveexec_b64 s[36:37], s[0:1]
	s_cbranch_execz .LBB0_1531
	global_load_ushort v126, v[2:3], off offset:16

.LBB0_1535:
	s_or_b64 exec, exec, s[36:37]
	v_cmp_gt_i32_e64 s[0:1], s4, v94
	s_and_saveexec_b64 s[36:37], s[0:1]
	s_cbranch_execz .LBB0_1537
	global_load_ushort v124, v[2:3], off offset:16

.LBB0_1541:
	s_or_b64 exec, exec, s[36:37]
	v_cmp_gt_i32_e64 s[0:1], s4, v95
	s_and_saveexec_b64 s[36:37], s[0:1]
	s_cbranch_execz .LBB0_1543
	global_load_ushort v122, v[2:3], off offset:16

.LBB0_1564:
	s_or_b64 exec, exec, s[0:1]
	s_waitcnt lgkmcnt(0)
	s_barrier
	global_load_dword v87, v136, s[30:31]
	global_load_dword v86, v137, s[30:31]
	global_load_dword v89, v135, s[30:31]
	global_load_dword v88, v135, s[34:35]
	s_and_saveexec_b64 s[0:1], vcc
	s_cbranch_execz .LBB0_1570
	s_waitcnt vmcnt(4)
	v_lshlrev_b32_e32 v2, 16, v165
	s_waitcnt vmcnt(0)
	v_fma_f32 v9, v89, v2, v88
	v_and_b32_e32 v2, 0xffff0000, v90
	v_lshlrev_b32_e32 v5, 16, v90
	v_mov_b32_e32 v4, v2
	v_pk_mul_f32 v[6:7], v[86:87], v[4:5]
	v_and_b32_e32 v3, 16, v90
	v_add_f32_e32 v4, v7, v9
	v_add_f32_e32 v9, v6, v4
	v_and_b32_e32 v4, 0xffff0000, v91
	v_lshlrev_b32_e32 v7, 16, v91
	v_mov_b32_e32 v6, v4
	v_fma_f32 v11, v89, v2, v88
	v_pk_mov_b32 v[2:3], v[6:7], v[2:3] op_sel:[1,0]
	v_fma_f32 v10, v89, v5, v88
	v_pk_mul_f32 v[2:3], v[86:87], v[2:3]
	v_and_b32_e32 v5, 16, v91
	v_add_f32_e32 v3, v3, v10
	v_add_f32_e32 v10, v2, v3
	v_pk_mul_f32 v[2:3], v[86:87], v[6:7]
	v_fma_f32 v12, v89, v7, v88
	v_add_f32_e32 v3, v3, v11
	v_add_f32_e32 v11, v2, v3
	v_and_b32_e32 v2, 0xffff0000, v92
	v_lshlrev_b32_e32 v7, 16, v92
	v_mov_b32_e32 v6, v2
	v_fma_f32 v13, v89, v4, v88
	v_pk_mov_b32 v[4:5], v[6:7], v[4:5] op_sel:[1,0]
	v_and_b32_e32 v3, 16, v92
	v_pk_mul_f32 v[4:5], v[86:87], v[4:5]
	v_lshrrev_b32_e32 v8, 8, v129
	v_add_f32_e32 v5, v5, v12
	v_add_f32_e32 v12, v4, v5
	v_pk_mul_f32 v[4:5], v[86:87], v[6:7]
	v_fma_f32 v7, v89, v7, v88
	v_add_f32_e32 v5, v5, v13
	v_add_f32_e32 v6, v4, v5
	v_and_b32_e32 v4, 0xffff0000, v93
	v_lshlrev_b32_e32 v5, 16, v93
	v_fma_f32 v13, v89, v2, v88
	v_pk_mov_b32 v[2:3], v[4:5], v[2:3] op_sel:[1,0]
	v_mov_b32_e32 v129, v4
	v_pk_mul_f32 v[2:3], v[86:87], v[2:3]
	s_nop 0
	v_add_f32_e32 v3, v3, v7
	v_add_f32_e32 v7, v2, v3
	v_pk_mul_f32 v[2:3], v[86:87], v[4:5]
	v_fma_f32 v5, v89, v5, v88
	v_add_f32_e32 v3, v3, v13
	v_add_f32_e32 v13, v2, v3
	s_waitcnt vmcnt(0)
	v_lshlrev_b32_e32 v128, 16, v128
	v_pk_mul_f32 v[2:3], v[128:129], v[86:87]
	s_nop 0
	v_add_f32_e32 v3, v3, v5
	v_add_f32_e32 v5, v2, v3
	v_cvt_pk_bf16_f32 v2, v9, v10
	v_cvt_pk_bf16_f32 v3, v11, v12
	v_cvt_pk_bf16_f32 v4, v6, v7
	v_mad_i32_i24 v6, v8, s71, v123
	v_lshl_add_u32 v6, v6, 1, 0
	v_add_u32_e32 v6, 0x14100, v6
	v_cvt_pk_bf16_f32 v5, v13, v5
	ds_write_b128 v6, v[2:5]
	s_or_b64 exec, exec, s[0:1]
	s_and_saveexec_b64 s[0:1], s[14:15]
	s_cbranch_execnz .LBB0_1571

.LBB0_1567:
	v_lshrrev_b32_e32 v2, 21, v153
	v_add_u32_e32 v2, v147, v2
	v_and_b32_e32 v2, 0x7ffff800, v2
	v_sub_u32_e32 v8, v147, v2
	v_add_u32_sdwa v2, v145, v149 dst_sel:DWORD dst_unused:UNUSED_PAD src0_sel:DWORD src1_sel:BYTE_3
	v_lshrrev_b32_e32 v9, 8, v2
	s_waitcnt vmcnt(4)
	v_lshlrev_b32_e32 v2, 16, v163
	s_waitcnt vmcnt(0)
	v_fma_f32 v10, v89, v2, v88
	v_and_b32_e32 v2, 0xffff0000, v76
	v_lshlrev_b32_e32 v5, 16, v76
	v_mov_b32_e32 v4, v2
	v_pk_mul_f32 v[6:7], v[86:87], v[4:5]
	v_and_b32_e32 v3, 16, v76
	v_add_f32_e32 v4, v7, v10
	v_add_f32_e32 v10, v6, v4
	v_and_b32_e32 v4, 0xffff0000, v77
	v_lshlrev_b32_e32 v7, 16, v77
	v_mov_b32_e32 v6, v4
	v_fma_f32 v12, v89, v2, v88
	v_pk_mov_b32 v[2:3], v[6:7], v[2:3] op_sel:[1,0]
	v_fma_f32 v11, v89, v5, v88
	v_pk_mul_f32 v[2:3], v[86:87], v[2:3]
	v_and_b32_e32 v5, 16, v77
	v_add_f32_e32 v3, v3, v11
	v_add_f32_e32 v11, v2, v3
	v_pk_mul_f32 v[2:3], v[86:87], v[6:7]
	v_fma_f32 v13, v89, v7, v88
	v_add_f32_e32 v3, v3, v12
	v_add_f32_e32 v12, v2, v3
	v_and_b32_e32 v2, 0xffff0000, v78
	v_lshlrev_b32_e32 v7, 16, v78
	v_mov_b32_e32 v6, v2
	v_fma_f32 v14, v89, v4, v88
	v_pk_mov_b32 v[4:5], v[6:7], v[4:5] op_sel:[1,0]
	v_and_b32_e32 v3, 16, v78
	v_pk_mul_f32 v[4:5], v[86:87], v[4:5]
	s_nop 0
	v_add_f32_e32 v5, v5, v13
	v_add_f32_e32 v13, v4, v5
	v_pk_mul_f32 v[4:5], v[86:87], v[6:7]
	v_fma_f32 v7, v89, v7, v88
	v_add_f32_e32 v5, v5, v14
	v_add_f32_e32 v6, v4, v5
	v_and_b32_e32 v4, 0xffff0000, v79
	v_lshlrev_b32_e32 v5, 16, v79
	v_fma_f32 v14, v89, v2, v88
	v_pk_mov_b32 v[2:3], v[4:5], v[2:3] op_sel:[1,0]
	v_mov_b32_e32 v125, v4
	v_pk_mul_f32 v[2:3], v[86:87], v[2:3]
	s_nop 0
	v_add_f32_e32 v3, v3, v7
	v_add_f32_e32 v7, v2, v3
	v_pk_mul_f32 v[2:3], v[86:87], v[4:5]
	v_fma_f32 v5, v89, v5, v88
	v_add_f32_e32 v3, v3, v14
	v_add_f32_e32 v14, v2, v3
	s_waitcnt vmcnt(0)
	v_lshlrev_b32_e32 v124, 16, v124
	v_pk_mul_f32 v[2:3], v[124:125], v[86:87]
	s_nop 0
	v_add_f32_e32 v3, v3, v5
	v_add_f32_e32 v5, v2, v3
	v_cvt_pk_bf16_f32 v2, v10, v11
	v_cvt_pk_bf16_f32 v3, v12, v13
	v_cvt_pk_bf16_f32 v4, v6, v7
	v_mad_i32_i24 v6, v9, s71, v8
	v_lshl_add_u32 v6, v6, 1, 0
	v_add_u32_e32 v6, 0x14100, v6
	v_cvt_pk_bf16_f32 v5, v14, v5
	ds_write_b128 v6, v[2:5]
	s_or_b64 exec, exec, s[0:1]
	s_and_saveexec_b64 s[0:1], s[10:11]
	s_cbranch_execnz .LBB0_1573
	s_branch .LBB0_1574

.LBB0_1571:
	v_lshrrev_b32_e32 v2, 21, v150
	v_add_u32_e32 v2, v144, v2
	v_and_b32_e32 v2, 0x7ffff800, v2
	v_sub_u32_e32 v8, v144, v2
	v_add_u32_sdwa v2, v127, v146 dst_sel:DWORD dst_unused:UNUSED_PAD src0_sel:DWORD src1_sel:BYTE_3
	v_lshrrev_b32_e32 v9, 8, v2
	s_waitcnt vmcnt(4)
	v_lshlrev_b32_e32 v2, 16, v164
	s_waitcnt vmcnt(0)
	v_fma_f32 v10, v89, v2, v88
	v_and_b32_e32 v2, 0xffff0000, v80
	v_lshlrev_b32_e32 v5, 16, v80
	v_mov_b32_e32 v4, v2
	v_pk_mul_f32 v[6:7], v[86:87], v[4:5]
	v_and_b32_e32 v3, 16, v80
	v_add_f32_e32 v4, v7, v10
	v_add_f32_e32 v10, v6, v4
	v_and_b32_e32 v4, 0xffff0000, v81
	v_lshlrev_b32_e32 v7, 16, v81
	v_mov_b32_e32 v6, v4
	v_fma_f32 v12, v89, v2, v88
	v_pk_mov_b32 v[2:3], v[6:7], v[2:3] op_sel:[1,0]
	v_fma_f32 v11, v89, v5, v88
	v_pk_mul_f32 v[2:3], v[86:87], v[2:3]
	v_and_b32_e32 v5, 16, v81
	v_add_f32_e32 v3, v3, v11
	v_add_f32_e32 v11, v2, v3
	v_pk_mul_f32 v[2:3], v[86:87], v[6:7]
	v_fma_f32 v13, v89, v7, v88
	v_add_f32_e32 v3, v3, v12
	v_add_f32_e32 v12, v2, v3
	v_and_b32_e32 v2, 0xffff0000, v82
	v_lshlrev_b32_e32 v7, 16, v82
	v_mov_b32_e32 v6, v2
	v_fma_f32 v14, v89, v4, v88
	v_pk_mov_b32 v[4:5], v[6:7], v[4:5] op_sel:[1,0]
	v_and_b32_e32 v3, 16, v82
	v_pk_mul_f32 v[4:5], v[86:87], v[4:5]
	s_nop 0
	v_add_f32_e32 v5, v5, v13
	v_add_f32_e32 v13, v4, v5
	v_pk_mul_f32 v[4:5], v[86:87], v[6:7]
	v_fma_f32 v7, v89, v7, v88
	v_add_f32_e32 v5, v5, v14
	v_add_f32_e32 v6, v4, v5
	v_and_b32_e32 v4, 0xffff0000, v83
	v_lshlrev_b32_e32 v5, 16, v83
	v_fma_f32 v14, v89, v2, v88
	v_pk_mov_b32 v[2:3], v[4:5], v[2:3] op_sel:[1,0]
	v_mov_b32_e32 v127, v4
	v_pk_mul_f32 v[2:3], v[86:87], v[2:3]
	s_nop 0
	v_add_f32_e32 v3, v3, v7
	v_add_f32_e32 v7, v2, v3
	v_pk_mul_f32 v[2:3], v[86:87], v[4:5]
	v_fma_f32 v5, v89, v5, v88
	v_add_f32_e32 v3, v3, v14
	v_add_f32_e32 v14, v2, v3
	s_waitcnt vmcnt(0)
	v_lshlrev_b32_e32 v126, 16, v126
	v_pk_mul_f32 v[2:3], v[126:127], v[86:87]
	s_nop 0
	v_add_f32_e32 v3, v3, v5
	v_add_f32_e32 v5, v2, v3
	v_cvt_pk_bf16_f32 v2, v10, v11
	v_cvt_pk_bf16_f32 v3, v12, v13
	v_cvt_pk_bf16_f32 v4, v6, v7
	v_mad_i32_i24 v6, v9, s71, v8
	v_lshl_add_u32 v6, v6, 1, 0
	v_add_u32_e32 v6, 0x14100, v6
	v_cvt_pk_bf16_f32 v5, v14, v5
	ds_write_b128 v6, v[2:5]
	s_or_b64 exec, exec, s[0:1]
	s_and_saveexec_b64 s[0:1], s[12:13]
	s_cbranch_execnz .LBB0_1567

.LBB0_1573:
	v_lshrrev_b32_e32 v2, 21, v154
	v_add_u32_e32 v2, v151, v2
	v_and_b32_e32 v2, 0x7ffff800, v2
	v_sub_u32_e32 v8, v151, v2
	v_add_u32_sdwa v2, v148, v152 dst_sel:DWORD dst_unused:UNUSED_PAD src0_sel:DWORD src1_sel:BYTE_3
	v_lshrrev_b32_e32 v9, 8, v2
	s_waitcnt vmcnt(4)
	v_lshlrev_b32_e32 v2, 16, v162
	s_waitcnt vmcnt(0)
	v_fma_f32 v10, v89, v2, v88
	v_and_b32_e32 v2, 0xffff0000, v66
	v_lshlrev_b32_e32 v5, 16, v66
	v_mov_b32_e32 v4, v2
	v_pk_mul_f32 v[6:7], v[86:87], v[4:5]
	v_and_b32_e32 v3, 16, v66
	v_add_f32_e32 v4, v7, v10
	v_add_f32_e32 v10, v6, v4
	v_and_b32_e32 v4, 0xffff0000, v67
	v_lshlrev_b32_e32 v7, 16, v67
	v_mov_b32_e32 v6, v4
	v_fma_f32 v12, v89, v2, v88
	v_pk_mov_b32 v[2:3], v[6:7], v[2:3] op_sel:[1,0]
	v_fma_f32 v11, v89, v5, v88
	v_pk_mul_f32 v[2:3], v[86:87], v[2:3]
	v_and_b32_e32 v5, 16, v67
	v_add_f32_e32 v3, v3, v11
	v_add_f32_e32 v11, v2, v3
	v_pk_mul_f32 v[2:3], v[86:87], v[6:7]
	v_fma_f32 v13, v89, v7, v88
	v_add_f32_e32 v3, v3, v12
	v_add_f32_e32 v12, v2, v3
	v_and_b32_e32 v2, 0xffff0000, v68
	v_lshlrev_b32_e32 v7, 16, v68
	v_mov_b32_e32 v6, v2
	v_fma_f32 v14, v89, v4, v88
	v_pk_mov_b32 v[4:5], v[6:7], v[4:5] op_sel:[1,0]
	v_and_b32_e32 v3, 16, v68
	v_pk_mul_f32 v[4:5], v[86:87], v[4:5]
	s_nop 0
	v_add_f32_e32 v5, v5, v13
	v_add_f32_e32 v13, v4, v5
	v_pk_mul_f32 v[4:5], v[86:87], v[6:7]
	v_fma_f32 v7, v89, v7, v88
	v_add_f32_e32 v5, v5, v14
	v_add_f32_e32 v6, v4, v5
	v_and_b32_e32 v4, 0xffff0000, v69
	v_lshlrev_b32_e32 v5, 16, v69
	v_fma_f32 v14, v89, v2, v88
	v_pk_mov_b32 v[2:3], v[4:5], v[2:3] op_sel:[1,0]
	v_mov_b32_e32 v123, v4
	v_pk_mul_f32 v[2:3], v[86:87], v[2:3]
	s_nop 0
	v_add_f32_e32 v3, v3, v7
	v_add_f32_e32 v7, v2, v3
	v_pk_mul_f32 v[2:3], v[86:87], v[4:5]
	v_fma_f32 v5, v89, v5, v88
	v_add_f32_e32 v3, v3, v14
	v_add_f32_e32 v14, v2, v3
	s_waitcnt vmcnt(0)
	v_lshlrev_b32_e32 v122, 16, v122
	v_pk_mul_f32 v[2:3], v[122:123], v[86:87]
	s_nop 0
	v_add_f32_e32 v3, v3, v5
	v_add_f32_e32 v5, v2, v3
	v_cvt_pk_bf16_f32 v2, v10, v11
	v_cvt_pk_bf16_f32 v3, v12, v13
	v_cvt_pk_bf16_f32 v4, v6, v7
	v_mad_i32_i24 v6, v9, s71, v8
	v_lshl_add_u32 v6, v6, 1, 0
	v_add_u32_e32 v6, 0x14100, v6
	v_cvt_pk_bf16_f32 v5, v14, v5
	ds_write_b128 v6, v[2:5]

.LBB0_1602:
	s_or_b64 exec, exec, s[16:17]
	s_and_saveexec_b64 s[16:17], s[10:11]
	s_cbranch_execz .LBB0_1604
	global_load_ushort v20, v[8:9], off offset:16

.LBB0_1608:
	s_or_b64 exec, exec, s[16:17]
	s_and_saveexec_b64 s[16:17], s[10:11]
	s_cbranch_execz .LBB0_1610
	global_load_ushort v18, v[22:23], off offset:16
.LBB0_1610:
	s_or_b64 exec, exec, s[16:17]

.LBB0_1613:
	s_or_b64 exec, exec, s[14:15]
	v_ashrrev_i32_e32 v2, 31, v39
	v_lshrrev_b32_e32 v42, 27, v2
	s_and_saveexec_b64 s[14:15], s[6:7]
	s_cbranch_execz .LBB0_1616
	v_add_u32_e32 v2, v39, v42
	v_ashrrev_i32_e32 v22, 5, v2
	v_mad_u64_u32 v[2:3], s[16:17], v22, s70, v[38:39]
	v_lshl_add_u32 v23, v2, 1, 0
	s_waitcnt vmcnt(0)
	v_lshlrev_b32_e32 v2, 16, v21
	v_fma_f32 v21, v140, v2, v141
	v_and_b32_e32 v2, 0xffff0000, v12
	v_lshlrev_b32_e32 v5, 16, v12
	v_mov_b32_e32 v4, v2
	v_pk_mul_f32 v[6:7], v[118:119], v[4:5]
	v_and_b32_e32 v3, 16, v12
	v_add_f32_e32 v4, v7, v21
	v_add_f32_e32 v12, v6, v4
	v_and_b32_e32 v4, 0xffff0000, v13
	v_lshlrev_b32_e32 v7, 16, v13
	v_mov_b32_e32 v6, v4
	v_fma_f32 v24, v140, v2, v141
	v_pk_mov_b32 v[2:3], v[6:7], v[2:3] op_sel:[1,0]
	v_fma_f32 v21, v140, v5, v141
	v_pk_mul_f32 v[2:3], v[118:119], v[2:3]
	v_and_b32_e32 v5, 16, v13
	v_add_f32_e32 v3, v3, v21
	v_add_f32_e32 v13, v2, v3
	v_pk_mul_f32 v[2:3], v[118:119], v[6:7]
	v_fma_f32 v21, v140, v7, v141
	v_add_f32_e32 v3, v3, v24
	v_add_f32_e32 v24, v2, v3
	v_and_b32_e32 v2, 0xffff0000, v14
	v_lshlrev_b32_e32 v7, 16, v14
	v_mov_b32_e32 v6, v2
	v_fma_f32 v25, v140, v4, v141
	v_pk_mov_b32 v[4:5], v[6:7], v[4:5] op_sel:[1,0]
	v_and_b32_e32 v3, 16, v14
	v_pk_mul_f32 v[4:5], v[118:119], v[4:5]
	s_nop 0
	v_add_f32_e32 v5, v5, v21
	v_add_f32_e32 v14, v4, v5
	v_pk_mul_f32 v[4:5], v[118:119], v[6:7]
	v_fma_f32 v21, v140, v2, v141
	v_add_f32_e32 v5, v5, v25
	v_add_f32_e32 v6, v4, v5
	v_and_b32_e32 v4, 0xffff0000, v15
	v_lshlrev_b32_e32 v5, 16, v15
	v_pk_mov_b32 v[2:3], v[4:5], v[2:3] op_sel:[1,0]
	v_fma_f32 v7, v140, v7, v141
	v_pk_mul_f32 v[2:3], v[118:119], v[2:3]
	v_fmac_f32_e32 v141, v140, v5
	v_add_f32_e32 v3, v3, v7
	v_add_f32_e32 v7, v2, v3
	v_pk_mul_f32 v[2:3], v[118:119], v[4:5]
	s_nop 0
	v_add_f32_e32 v3, v3, v21
	v_mov_b32_e32 v21, v4
	v_add_f32_e32 v15, v2, v3
	s_waitcnt vmcnt(0)
	v_lshlrev_b32_e32 v20, 16, v20
	v_pk_mul_f32 v[2:3], v[118:119], v[20:21]
	s_nop 0
	v_add_f32_e32 v3, v3, v141
	v_add_f32_e32 v5, v2, v3
	v_cvt_pk_bf16_f32 v2, v12, v13
	v_cvt_pk_bf16_f32 v3, v24, v14
	v_cvt_pk_bf16_f32 v4, v6, v7
	v_cvt_pk_bf16_f32 v5, v15, v5
	ds_write_b128 v23, v[2:5] offset:33920
	v_mad_u64_u32 v[2:3], s[16:17], v22, s71, v[38:39]
	v_lshl_add_u32 v2, v2, 1, 0
	v_add_u32_e32 v12, 0x14100, v2
	v_lshlrev_b32_e32 v2, 16, v19
	v_fma_f32 v13, v143, v2, v142
	v_and_b32_e32 v2, 0xffff0000, v8
	v_lshlrev_b32_e32 v5, 16, v8
	v_mov_b32_e32 v4, v2
	v_pk_mul_f32 v[6:7], v[120:121], v[4:5]
	v_and_b32_e32 v3, 16, v8
	v_add_f32_e32 v4, v7, v13
	v_add_f32_e32 v8, v6, v4
	v_and_b32_e32 v4, 0xffff0000, v9
	v_lshlrev_b32_e32 v7, 16, v9
	v_mov_b32_e32 v6, v4
	v_fma_f32 v14, v143, v2, v142
	v_pk_mov_b32 v[2:3], v[6:7], v[2:3] op_sel:[1,0]
	v_fma_f32 v13, v143, v5, v142
	v_pk_mul_f32 v[2:3], v[120:121], v[2:3]
	v_and_b32_e32 v5, 16, v9
	v_add_f32_e32 v3, v3, v13
	v_add_f32_e32 v9, v2, v3
	v_pk_mul_f32 v[2:3], v[120:121], v[6:7]
	v_fma_f32 v15, v143, v4, v142
	v_add_f32_e32 v3, v3, v14
	v_add_f32_e32 v13, v2, v3
	v_and_b32_e32 v2, 0xffff0000, v10
	v_fma_f32 v14, v143, v7, v142
	v_lshlrev_b32_e32 v7, 16, v10
	v_mov_b32_e32 v6, v2
	v_pk_mov_b32 v[4:5], v[6:7], v[4:5] op_sel:[1,0]
	v_and_b32_e32 v3, 16, v10
	v_pk_mul_f32 v[4:5], v[120:121], v[4:5]
	s_mov_b64 s[16:17], 0
	v_add_f32_e32 v5, v5, v14
	v_add_f32_e32 v10, v4, v5
	v_pk_mul_f32 v[4:5], v[120:121], v[6:7]
	v_fma_f32 v14, v143, v2, v142
	v_add_f32_e32 v5, v5, v15
	v_add_f32_e32 v6, v4, v5
	v_and_b32_e32 v4, 0xffff0000, v11
	v_lshlrev_b32_e32 v5, 16, v11
	v_pk_mov_b32 v[2:3], v[4:5], v[2:3] op_sel:[1,0]
	v_fma_f32 v7, v143, v7, v142
	v_pk_mul_f32 v[2:3], v[120:121], v[2:3]
	v_mov_b32_e32 v19, v4
	v_add_f32_e32 v3, v3, v7
	v_add_f32_e32 v7, v2, v3
	v_pk_mul_f32 v[2:3], v[120:121], v[4:5]
	v_fmac_f32_e32 v142, v143, v5
	v_add_f32_e32 v3, v3, v14
	v_add_f32_e32 v11, v2, v3
	s_waitcnt vmcnt(0)
	v_lshlrev_b32_e32 v18, 16, v18
	v_pk_mul_f32 v[2:3], v[120:121], v[18:19]
	s_nop 0
	v_add_f32_e32 v3, v3, v142
	v_add_f32_e32 v5, v2, v3
	v_cvt_pk_bf16_f32 v2, v8, v9
	v_cvt_pk_bf16_f32 v3, v13, v10
	v_cvt_pk_bf16_f32 v4, v6, v7
	v_cvt_pk_bf16_f32 v5, v11, v5
	ds_write_b128 v12, v[2:5]
	v_mov_b32_e32 v2, v36
	v_mov_b32_e32 v3, v39

.LBB0_1625:
	s_or_b64 exec, exec, s[12:13]
	s_and_saveexec_b64 s[12:13], s[10:11]
	s_cbranch_execz .LBB0_1627
	global_load_ushort v40, v[2:3], off offset:16

.LBB0_1636:
	s_or_b64 exec, exec, s[8:9]
	s_waitcnt lgkmcnt(0)
	s_barrier
	s_and_saveexec_b64 s[0:1], s[6:7]
	s_cbranch_execz .LBB0_1638
	v_add_u32_e32 v2, v39, v42
	v_ashrrev_i32_e32 v2, 5, v2
	v_mad_u64_u32 v[2:3], s[8:9], v2, s71, v[38:39]
	v_lshl_add_u32 v2, v2, 1, 0
	v_add_u32_e32 v8, 0x14100, v2
	v_lshlrev_b32_e32 v2, 16, v51
	v_fma_f32 v9, v89, v2, v88
	v_and_b32_e32 v2, 0xffff0000, v22
	v_lshlrev_b32_e32 v5, 16, v22
	v_mov_b32_e32 v4, v2
	v_pk_mul_f32 v[6:7], v[86:87], v[4:5]
	v_and_b32_e32 v3, 16, v22
	v_add_f32_e32 v4, v7, v9
	v_add_f32_e32 v9, v6, v4
	v_and_b32_e32 v4, 0xffff0000, v23
	v_lshlrev_b32_e32 v7, 16, v23
	v_mov_b32_e32 v6, v4
	v_fma_f32 v11, v89, v2, v88
	v_pk_mov_b32 v[2:3], v[6:7], v[2:3] op_sel:[1,0]
	v_fma_f32 v10, v89, v5, v88
	v_pk_mul_f32 v[2:3], v[86:87], v[2:3]
	v_and_b32_e32 v5, 16, v23
	v_add_f32_e32 v3, v3, v10
	v_add_f32_e32 v10, v2, v3
	v_pk_mul_f32 v[2:3], v[86:87], v[6:7]
	v_fma_f32 v12, v89, v7, v88
	v_add_f32_e32 v3, v3, v11
	v_add_f32_e32 v11, v2, v3
	v_and_b32_e32 v2, 0xffff0000, v24
	v_lshlrev_b32_e32 v7, 16, v24
	v_mov_b32_e32 v6, v2
	v_fma_f32 v13, v89, v4, v88
	v_pk_mov_b32 v[4:5], v[6:7], v[4:5] op_sel:[1,0]
	v_and_b32_e32 v3, 16, v24
	v_pk_mul_f32 v[4:5], v[86:87], v[4:5]
	s_nop 0
	v_add_f32_e32 v5, v5, v12
	v_add_f32_e32 v12, v4, v5
	v_pk_mul_f32 v[4:5], v[86:87], v[6:7]
	v_fma_f32 v7, v89, v7, v88
	v_add_f32_e32 v5, v5, v13
	v_add_f32_e32 v6, v4, v5
	v_and_b32_e32 v4, 0xffff0000, v25
	v_lshlrev_b32_e32 v5, 16, v25
	v_fma_f32 v13, v89, v2, v88
	v_pk_mov_b32 v[2:3], v[4:5], v[2:3] op_sel:[1,0]
	v_mov_b32_e32 v41, v4
	v_pk_mul_f32 v[2:3], v[86:87], v[2:3]
	v_fmac_f32_e32 v88, v89, v5
	v_add_f32_e32 v3, v3, v7
	v_add_f32_e32 v7, v2, v3
	v_pk_mul_f32 v[2:3], v[86:87], v[4:5]
	s_nop 0
	v_add_f32_e32 v3, v3, v13
	v_add_f32_e32 v13, v2, v3
	s_waitcnt vmcnt(0)
	v_lshlrev_b32_e32 v40, 16, v40
	v_pk_mul_f32 v[2:3], v[86:87], v[40:41]
	s_nop 0
	v_add_f32_e32 v3, v3, v88
	v_add_f32_e32 v5, v2, v3
	v_cvt_pk_bf16_f32 v2, v9, v10
	v_cvt_pk_bf16_f32 v3, v11, v12
	v_cvt_pk_bf16_f32 v4, v6, v7
	v_cvt_pk_bf16_f32 v5, v13, v5
	ds_write_b128 v8, v[2:5]

.LBB0_3340:
	s_or_b64 exec, exec, s[12:13]
	v_cmp_gt_i32_e64 s[0:1], s49, v119
	s_and_saveexec_b64 s[12:13], s[0:1]
	s_cbranch_execz .LBB0_3342
	global_load_ushort v68, v[2:3], off offset:16

.LBB0_3346:
	s_or_b64 exec, exec, s[12:13]
	v_cmp_gt_i32_e64 s[0:1], s49, v78
	s_and_saveexec_b64 s[12:13], s[0:1]
	s_cbranch_execz .LBB0_3348
	global_load_ushort v66, v[2:3], off offset:16

.LBB0_3352:
	s_or_b64 exec, exec, s[24:25]
	v_cmp_gt_i32_e64 s[0:1], s49, v94
	s_and_saveexec_b64 s[24:25], s[0:1]
	s_cbranch_execz .LBB0_3354
	global_load_ushort v64, v[2:3], off offset:16

.LBB0_3358:
	s_or_b64 exec, exec, s[22:23]
	v_cmp_gt_i32_e64 s[0:1], s49, v95
	s_and_saveexec_b64 s[22:23], s[0:1]
	s_cbranch_execz .LBB0_3360
	global_load_ushort v62, v[2:3], off offset:16

.LBB0_3364:
	s_or_b64 exec, exec, s[26:27]
	v_cmp_gt_i32_e64 s[0:1], s49, v119
	s_and_saveexec_b64 s[26:27], s[0:1]
	s_cbranch_execz .LBB0_3366
	global_load_ushort v60, v[2:3], off offset:16

.LBB0_3370:
	s_or_b64 exec, exec, s[26:27]
	v_cmp_gt_i32_e64 s[0:1], s49, v78
	s_and_saveexec_b64 s[26:27], s[0:1]
	s_cbranch_execz .LBB0_3372
	global_load_ushort v58, v[2:3], off offset:16

.LBB0_3376:
	s_or_b64 exec, exec, s[26:27]
	v_cmp_gt_i32_e64 s[0:1], s49, v94
	s_and_saveexec_b64 s[26:27], s[0:1]
	s_cbranch_execz .LBB0_3378
	global_load_ushort v56, v[2:3], off offset:16

.LBB0_3382:
	s_or_b64 exec, exec, s[22:23]
	v_cmp_gt_i32_e64 s[0:1], s49, v95
	s_and_saveexec_b64 s[22:23], s[0:1]
	s_cbranch_execz .LBB0_3384
	global_load_ushort v54, v[70:71], off offset:16
.LBB0_3384:
	s_or_b64 exec, exec, s[22:23]
	s_or_b64 exec, exec, s[24:25]
	v_lshl_add_u32 v121, v135, 4, 0
	s_and_saveexec_b64 s[0:1], s[6:7]
	s_cbranch_execnz .LBB0_3400

.LBB0_3387:
	s_or_b64 exec, exec, s[0:1]
	s_lshl_b64 s[0:1], s[18:19], 2
	s_add_u32 s22, s31, s0
	s_addc_u32 s23, s34, s1
	s_add_u32 s24, s35, s0
	s_addc_u32 s25, s36, s1
	global_load_dword v24, v115, s[22:23]
	global_load_dword v23, v126, s[22:23]
	global_load_dword v25, v115, s[24:25]
	global_load_dword v22, v127, s[22:23]
	v_ashrrev_i32_e32 v26, 31, v135
	v_add_u32_sdwa v125, v135, v26 dst_sel:DWORD dst_unused:UNUSED_PAD src0_sel:DWORD src1_sel:BYTE_3
	s_and_saveexec_b64 s[0:1], vcc
	s_cbranch_execz .LBB0_3389
	s_waitcnt vmcnt(4)
	v_lshlrev_b32_e32 v26, 16, v67
	s_waitcnt vmcnt(1)
	v_fma_f32 v41, v24, v26, v25
	v_and_b32_e32 v26, 0xffff0000, v42
	v_lshlrev_b32_e32 v37, 16, v42
	v_mov_b32_e32 v36, v26
	s_waitcnt vmcnt(0)
	v_pk_mul_f32 v[38:39], v[22:23], v[36:37]
	v_and_b32_e32 v27, 16, v42
	v_add_f32_e32 v36, v39, v41
	v_add_f32_e32 v41, v38, v36
	v_and_b32_e32 v36, 0xffff0000, v43
	v_lshlrev_b32_e32 v39, 16, v43
	v_mov_b32_e32 v38, v36
	v_fma_f32 v67, v24, v26, v25
	v_pk_mov_b32 v[26:27], v[38:39], v[26:27] op_sel:[1,0]
	v_fma_f32 v42, v24, v37, v25
	v_pk_mul_f32 v[26:27], v[22:23], v[26:27]
	v_and_b32_e32 v37, 16, v43
	v_add_f32_e32 v27, v27, v42
	v_add_f32_e32 v42, v26, v27
	v_pk_mul_f32 v[26:27], v[22:23], v[38:39]
	v_fma_f32 v69, v24, v36, v25
	v_add_f32_e32 v27, v27, v67
	v_add_f32_e32 v43, v26, v27
	v_and_b32_e32 v26, 0xffff0000, v44
	v_fma_f32 v67, v24, v39, v25
	v_lshlrev_b32_e32 v39, 16, v44
	v_mov_b32_e32 v38, v26
	v_pk_mov_b32 v[36:37], v[38:39], v[36:37] op_sel:[1,0]
	v_and_b32_e32 v27, 16, v44
	v_pk_mul_f32 v[36:37], v[22:23], v[36:37]
	v_lshrrev_b32_e32 v40, 8, v125
	v_add_f32_e32 v37, v37, v67
	v_add_f32_e32 v44, v36, v37
	v_pk_mul_f32 v[36:37], v[22:23], v[38:39]
	v_fma_f32 v67, v24, v26, v25
	v_add_f32_e32 v37, v37, v69
	v_add_f32_e32 v38, v36, v37
	v_and_b32_e32 v36, 0xffff0000, v45
	v_lshlrev_b32_e32 v37, 16, v45
	v_pk_mov_b32 v[26:27], v[36:37], v[26:27] op_sel:[1,0]
	v_fma_f32 v39, v24, v39, v25
	v_pk_mul_f32 v[26:27], v[22:23], v[26:27]
	v_mov_b32_e32 v69, v36
	v_add_f32_e32 v27, v27, v39
	v_add_f32_e32 v39, v26, v27
	v_pk_mul_f32 v[26:27], v[22:23], v[36:37]
	v_fma_f32 v37, v24, v37, v25
	v_add_f32_e32 v27, v27, v67
	v_add_f32_e32 v45, v26, v27
	s_waitcnt vmcnt(0)
	v_lshlrev_b32_e32 v68, 16, v68
	v_pk_mul_f32 v[26:27], v[68:69], v[22:23]
	v_cvt_pk_bf16_f32 v36, v41, v42
	s_nop 0
	v_add_f32_e32 v27, v27, v37
	v_add_f32_e32 v26, v26, v27
	v_cvt_pk_bf16_f32 v37, v43, v44
	v_cvt_pk_bf16_f32 v38, v38, v39
	v_cvt_pk_bf16_f32 v39, v45, v26
	v_mad_i32_i24 v26, v40, s55, v119
	v_lshl_add_u32 v26, v26, 1, 0
	ds_write_b128 v26, v[36:39] offset:33920
.LBB0_3389:
	s_or_b64 exec, exec, s[0:1]
	v_add_u32_e32 v123, 0x200, v135
	v_lshlrev_b32_e32 v136, 3, v123
	v_bfe_i32 v142, v123, 28, 1
	v_ashrrev_i32_e32 v138, 31, v123
	s_and_saveexec_b64 s[0:1], s[14:15]
	s_cbranch_execz .LBB0_3391
	v_lshrrev_b32_e32 v26, 21, v142
	v_add_u32_e32 v26, v136, v26
	v_and_b32_e32 v26, 0x7ffff800, v26
	v_sub_u32_e32 v40, v136, v26
	v_add_u32_sdwa v26, v123, v138 dst_sel:DWORD dst_unused:UNUSED_PAD src0_sel:DWORD src1_sel:BYTE_3
	v_lshrrev_b32_e32 v41, 8, v26
	s_waitcnt vmcnt(4)
	v_lshlrev_b32_e32 v26, 16, v65
	s_waitcnt vmcnt(1)
	v_fma_f32 v42, v24, v26, v25
	v_and_b32_e32 v26, 0xffff0000, v32
	v_lshlrev_b32_e32 v37, 16, v32
	v_mov_b32_e32 v36, v26
	s_waitcnt vmcnt(0)
	v_pk_mul_f32 v[38:39], v[22:23], v[36:37]
	v_and_b32_e32 v27, 16, v32
	v_add_f32_e32 v32, v39, v42
	v_and_b32_e32 v36, 0xffff0000, v33
	v_add_f32_e32 v38, v38, v32
	v_fma_f32 v39, v24, v37, v25
	v_and_b32_e32 v37, 16, v33
	v_lshlrev_b32_e32 v33, 16, v33
	v_mov_b32_e32 v32, v36
	v_fma_f32 v42, v24, v26, v25
	v_pk_mov_b32 v[26:27], v[32:33], v[26:27] op_sel:[1,0]
	v_fma_f32 v43, v24, v33, v25
	v_pk_mul_f32 v[26:27], v[22:23], v[26:27]
	v_fma_f32 v44, v24, v36, v25
	v_add_f32_e32 v27, v27, v39
	v_add_f32_e32 v39, v26, v27
	v_pk_mul_f32 v[26:27], v[22:23], v[32:33]
	v_lshlrev_b32_e32 v33, 16, v34
	v_add_f32_e32 v27, v27, v42
	v_add_f32_e32 v42, v26, v27
	v_and_b32_e32 v26, 0xffff0000, v34
	v_mov_b32_e32 v32, v26
	v_pk_mov_b32 v[36:37], v[32:33], v[36:37] op_sel:[1,0]
	v_and_b32_e32 v27, 16, v34
	v_pk_mul_f32 v[36:37], v[22:23], v[36:37]
	s_nop 0
	v_add_f32_e32 v34, v37, v43
	v_add_f32_e32 v34, v36, v34
	v_pk_mul_f32 v[36:37], v[22:23], v[32:33]
	v_fma_f32 v43, v24, v26, v25
	v_add_f32_e32 v32, v37, v44
	v_add_f32_e32 v36, v36, v32
	v_fma_f32 v37, v24, v33, v25
	v_and_b32_e32 v32, 0xffff0000, v35
	v_lshlrev_b32_e32 v33, 16, v35
	v_pk_mov_b32 v[26:27], v[32:33], v[26:27] op_sel:[1,0]
	v_mov_b32_e32 v67, v32
	v_pk_mul_f32 v[26:27], v[22:23], v[26:27]
	s_nop 0
	v_add_f32_e32 v27, v27, v37
	v_add_f32_e32 v35, v26, v27
	v_pk_mul_f32 v[26:27], v[22:23], v[32:33]
	v_fma_f32 v33, v24, v33, v25
	v_add_f32_e32 v27, v27, v43
	v_add_f32_e32 v37, v26, v27
	s_waitcnt vmcnt(0)
	v_lshlrev_b32_e32 v66, 16, v66
	v_pk_mul_f32 v[26:27], v[66:67], v[22:23]
	v_cvt_pk_bf16_f32 v32, v38, v39
	s_nop 0
	v_add_f32_e32 v27, v27, v33
	v_add_f32_e32 v26, v26, v27
	v_cvt_pk_bf16_f32 v33, v42, v34
	v_cvt_pk_bf16_f32 v34, v36, v35
	v_cvt_pk_bf16_f32 v35, v37, v26
	v_mad_i32_i24 v26, v41, s55, v40
	v_lshl_add_u32 v26, v26, 1, 0
	ds_write_b128 v26, v[32:35] offset:33920
.LBB0_3391:
	s_or_b64 exec, exec, s[0:1]
	v_add_u32_e32 v137, 0x400, v135
	v_lshlrev_b32_e32 v139, 3, v137
	v_bfe_i32 v145, v137, 28, 1
	v_ashrrev_i32_e32 v141, 31, v137
	s_and_saveexec_b64 s[0:1], s[12:13]
	s_cbranch_execz .LBB0_3393
	v_lshrrev_b32_e32 v26, 21, v145
	v_add_u32_e32 v26, v139, v26
	v_and_b32_e32 v26, 0x7ffff800, v26
	v_sub_u32_e32 v36, v139, v26
	v_add_u32_sdwa v26, v137, v141 dst_sel:DWORD dst_unused:UNUSED_PAD src0_sel:DWORD src1_sel:BYTE_3
	v_lshrrev_b32_e32 v37, 8, v26
	s_waitcnt vmcnt(4)
	v_lshlrev_b32_e32 v26, 16, v63
	s_waitcnt vmcnt(1)
	v_fma_f32 v38, v24, v26, v25
	v_and_b32_e32 v26, 0xffff0000, v28
	v_lshlrev_b32_e32 v33, 16, v28
	v_mov_b32_e32 v32, v26
	s_waitcnt vmcnt(0)
	v_pk_mul_f32 v[34:35], v[22:23], v[32:33]
	v_and_b32_e32 v27, 16, v28
	v_add_f32_e32 v28, v35, v38
	v_and_b32_e32 v32, 0xffff0000, v29
	v_add_f32_e32 v34, v34, v28
	v_fma_f32 v35, v24, v33, v25
	v_and_b32_e32 v33, 16, v29
	v_lshlrev_b32_e32 v29, 16, v29
	v_mov_b32_e32 v28, v32
	v_fma_f32 v38, v24, v26, v25
	v_pk_mov_b32 v[26:27], v[28:29], v[26:27] op_sel:[1,0]
	v_fma_f32 v39, v24, v29, v25
	v_pk_mul_f32 v[26:27], v[22:23], v[26:27]
	v_fma_f32 v40, v24, v32, v25
	v_add_f32_e32 v27, v27, v35
	v_add_f32_e32 v35, v26, v27
	v_pk_mul_f32 v[26:27], v[22:23], v[28:29]
	v_lshlrev_b32_e32 v29, 16, v30
	v_add_f32_e32 v27, v27, v38
	v_add_f32_e32 v38, v26, v27
	v_and_b32_e32 v26, 0xffff0000, v30
	v_mov_b32_e32 v28, v26
	v_pk_mov_b32 v[32:33], v[28:29], v[32:33] op_sel:[1,0]
	v_and_b32_e32 v27, 16, v30
	v_pk_mul_f32 v[32:33], v[22:23], v[32:33]
	s_nop 0
	v_add_f32_e32 v30, v33, v39
	v_add_f32_e32 v30, v32, v30
	v_pk_mul_f32 v[32:33], v[22:23], v[28:29]
	v_fma_f32 v39, v24, v26, v25
	v_add_f32_e32 v28, v33, v40
	v_add_f32_e32 v32, v32, v28
	v_fma_f32 v33, v24, v29, v25
	v_and_b32_e32 v28, 0xffff0000, v31
	v_lshlrev_b32_e32 v29, 16, v31
	v_pk_mov_b32 v[26:27], v[28:29], v[26:27] op_sel:[1,0]
	v_mov_b32_e32 v65, v28
	v_pk_mul_f32 v[26:27], v[22:23], v[26:27]
	s_nop 0
	v_add_f32_e32 v27, v27, v33
	v_add_f32_e32 v31, v26, v27
	v_pk_mul_f32 v[26:27], v[22:23], v[28:29]
	v_fma_f32 v29, v24, v29, v25
	v_add_f32_e32 v27, v27, v39
	v_add_f32_e32 v33, v26, v27
	s_waitcnt vmcnt(0)
	v_lshlrev_b32_e32 v64, 16, v64
	v_pk_mul_f32 v[26:27], v[64:65], v[22:23]
	s_nop 0
	v_add_f32_e32 v27, v27, v29
	v_add_f32_e32 v29, v26, v27
	v_cvt_pk_bf16_f32 v26, v34, v35
	v_cvt_pk_bf16_f32 v27, v38, v30
	v_mad_i32_i24 v30, v37, s55, v36
	v_lshl_add_u32 v30, v30, 1, 0
	v_cvt_pk_bf16_f32 v28, v32, v31
	v_cvt_pk_bf16_f32 v29, v33, v29
	ds_write_b128 v30, v[26:29] offset:33920
.LBB0_3393:
	s_or_b64 exec, exec, s[0:1]
	v_add_u32_e32 v140, 0x600, v135
	v_lshlrev_b32_e32 v143, 3, v140
	v_bfe_i32 v146, v140, 28, 1
	v_ashrrev_i32_e32 v144, 31, v140
	s_and_saveexec_b64 s[0:1], s[10:11]
	s_cbranch_execz .LBB0_3395
	v_lshrrev_b32_e32 v26, 21, v146
	v_add_u32_e32 v26, v143, v26
	v_and_b32_e32 v26, 0x7ffff800, v26
	s_waitcnt vmcnt(4)
	v_sub_u32_e32 v32, v143, v26
	v_add_u32_sdwa v26, v140, v144 dst_sel:DWORD dst_unused:UNUSED_PAD src0_sel:DWORD src1_sel:BYTE_3
	v_lshrrev_b32_e32 v33, 8, v26
	v_lshlrev_b32_e32 v26, 16, v61
	s_waitcnt vmcnt(1)
	v_fma_f32 v34, v24, v26, v25
	v_and_b32_e32 v26, 0xffff0000, v18
	v_lshlrev_b32_e32 v29, 16, v18
	v_mov_b32_e32 v28, v26
	s_waitcnt vmcnt(0)
	v_pk_mul_f32 v[30:31], v[22:23], v[28:29]
	v_and_b32_e32 v27, 16, v18
	v_add_f32_e32 v18, v31, v34
	v_and_b32_e32 v28, 0xffff0000, v19
	v_add_f32_e32 v30, v30, v18
	v_fma_f32 v31, v24, v29, v25
	v_and_b32_e32 v29, 16, v19
	v_lshlrev_b32_e32 v19, 16, v19
	v_mov_b32_e32 v18, v28
	v_fma_f32 v34, v24, v26, v25
	v_pk_mov_b32 v[26:27], v[18:19], v[26:27] op_sel:[1,0]
	v_fma_f32 v36, v24, v28, v25
	v_pk_mul_f32 v[26:27], v[22:23], v[26:27]
	v_fma_f32 v35, v24, v19, v25
	v_add_f32_e32 v27, v27, v31
	v_add_f32_e32 v31, v26, v27
	v_pk_mul_f32 v[26:27], v[22:23], v[18:19]
	v_and_b32_e32 v19, 16, v20
	v_add_f32_e32 v18, v27, v34
	v_add_f32_e32 v34, v26, v18
	v_and_b32_e32 v18, 0xffff0000, v20
	v_lshlrev_b32_e32 v27, 16, v20
	v_mov_b32_e32 v26, v18
	v_pk_mov_b32 v[28:29], v[26:27], v[28:29] op_sel:[1,0]
	s_nop 0
	v_pk_mul_f32 v[28:29], v[22:23], v[28:29]
	s_nop 0
	v_add_f32_e32 v20, v29, v35
	v_add_f32_e32 v35, v28, v20
	v_pk_mul_f32 v[28:29], v[22:23], v[26:27]
	v_fma_f32 v27, v24, v27, v25
	v_add_f32_e32 v20, v29, v36
	v_add_f32_e32 v26, v28, v20
	v_and_b32_e32 v20, 0xffff0000, v21
	v_lshlrev_b32_e32 v21, 16, v21
	v_fma_f32 v28, v24, v18, v25
	v_pk_mov_b32 v[18:19], v[20:21], v[18:19] op_sel:[1,0]
	v_mov_b32_e32 v63, v20
	v_pk_mul_f32 v[18:19], v[22:23], v[18:19]
	v_fmac_f32_e32 v25, v24, v21
	v_add_f32_e32 v19, v19, v27
	v_add_f32_e32 v27, v18, v19
	v_pk_mul_f32 v[18:19], v[22:23], v[20:21]
	s_nop 0
	v_add_f32_e32 v19, v19, v28
	v_add_f32_e32 v28, v18, v19
	s_waitcnt vmcnt(0)
	v_lshlrev_b32_e32 v62, 16, v62
	v_pk_mul_f32 v[18:19], v[62:63], v[22:23]
	v_mad_i32_i24 v22, v33, s55, v32
	v_add_f32_e32 v19, v19, v25
	v_add_f32_e32 v21, v18, v19
	v_lshl_add_u32 v22, v22, 1, 0
	v_cvt_pk_bf16_f32 v18, v30, v31
	v_cvt_pk_bf16_f32 v19, v34, v35
	v_cvt_pk_bf16_f32 v20, v26, v27
	v_cvt_pk_bf16_f32 v21, v28, v21
	ds_write_b128 v22, v[18:21] offset:33920
.LBB0_3395:
	s_or_b64 exec, exec, s[0:1]
	global_load_dword v19, v129, s[22:23]
	global_load_dword v18, v130, s[22:23]
	global_load_dword v21, v128, s[22:23]
	global_load_dword v20, v128, s[24:25]
	s_and_saveexec_b64 s[0:1], vcc
	s_cbranch_execz .LBB0_3401
	s_waitcnt vmcnt(4)
	v_lshlrev_b32_e32 v22, 16, v59
	s_waitcnt vmcnt(0)
	v_fma_f32 v29, v21, v22, v20
	v_and_b32_e32 v22, 0xffff0000, v14
	v_lshlrev_b32_e32 v25, 16, v14
	v_mov_b32_e32 v24, v22
	v_pk_mul_f32 v[26:27], v[18:19], v[24:25]
	v_and_b32_e32 v23, 16, v14
	v_add_f32_e32 v14, v27, v29
	v_and_b32_e32 v24, 0xffff0000, v15
	v_add_f32_e32 v26, v26, v14
	v_fma_f32 v27, v21, v25, v20
	v_and_b32_e32 v25, 16, v15
	v_lshlrev_b32_e32 v15, 16, v15
	v_mov_b32_e32 v14, v24
	v_fma_f32 v29, v21, v22, v20
	v_pk_mov_b32 v[22:23], v[14:15], v[22:23] op_sel:[1,0]
	v_fma_f32 v31, v21, v24, v20
	v_pk_mul_f32 v[22:23], v[18:19], v[22:23]
	v_fma_f32 v30, v21, v15, v20
	v_add_f32_e32 v23, v23, v27
	v_add_f32_e32 v27, v22, v23
	v_pk_mul_f32 v[22:23], v[18:19], v[14:15]
	v_and_b32_e32 v15, 16, v16
	v_add_f32_e32 v14, v23, v29
	v_add_f32_e32 v29, v22, v14
	v_and_b32_e32 v14, 0xffff0000, v16
	v_lshlrev_b32_e32 v23, 16, v16
	v_mov_b32_e32 v22, v14
	v_pk_mov_b32 v[24:25], v[22:23], v[24:25] op_sel:[1,0]
	v_lshrrev_b32_e32 v28, 8, v125
	v_pk_mul_f32 v[24:25], v[18:19], v[24:25]
	s_nop 0
	v_add_f32_e32 v16, v25, v30
	v_add_f32_e32 v30, v24, v16
	v_pk_mul_f32 v[24:25], v[18:19], v[22:23]
	v_fma_f32 v23, v21, v23, v20
	v_add_f32_e32 v16, v25, v31
	v_add_f32_e32 v22, v24, v16
	v_and_b32_e32 v16, 0xffff0000, v17
	v_lshlrev_b32_e32 v17, 16, v17
	v_fma_f32 v24, v21, v14, v20
	v_pk_mov_b32 v[14:15], v[16:17], v[14:15] op_sel:[1,0]
	v_mov_b32_e32 v61, v16
	v_pk_mul_f32 v[14:15], v[18:19], v[14:15]
	s_nop 0
	v_add_f32_e32 v15, v15, v23
	v_add_f32_e32 v23, v14, v15
	v_pk_mul_f32 v[14:15], v[18:19], v[16:17]
	v_fma_f32 v17, v21, v17, v20
	v_add_f32_e32 v15, v15, v24
	v_add_f32_e32 v24, v14, v15
	s_waitcnt vmcnt(0)
	v_lshlrev_b32_e32 v60, 16, v60
	v_pk_mul_f32 v[14:15], v[60:61], v[18:19]
	s_nop 0
	v_add_f32_e32 v15, v15, v17
	v_add_f32_e32 v17, v14, v15
	v_cvt_pk_bf16_f32 v14, v26, v27
	v_cvt_pk_bf16_f32 v15, v29, v30
	v_cvt_pk_bf16_f32 v16, v22, v23
	v_mad_i32_i24 v22, v28, s58, v119
	v_lshl_add_u32 v22, v22, 1, 0
	v_add_u32_e32 v22, 0x14100, v22
	v_cvt_pk_bf16_f32 v17, v24, v17
	ds_write_b128 v22, v[14:17]
	s_or_b64 exec, exec, s[0:1]
	s_and_saveexec_b64 s[0:1], s[14:15]
	s_cbranch_execnz .LBB0_3402

.LBB0_3398:
	s_waitcnt vmcnt(8)
	v_lshrrev_b32_e32 v10, 21, v145
	v_add_u32_e32 v10, v139, v10
	v_and_b32_e32 v10, 0x7ffff800, v10
	v_sub_u32_e32 v16, v139, v10
	v_add_u32_sdwa v10, v137, v141 dst_sel:DWORD dst_unused:UNUSED_PAD src0_sel:DWORD src1_sel:BYTE_3
	v_lshrrev_b32_e32 v17, 8, v10
	v_lshlrev_b32_e32 v10, 16, v55
	s_waitcnt vmcnt(0)
	v_fma_f32 v22, v21, v10, v20
	v_and_b32_e32 v10, 0xffff0000, v6
	v_lshlrev_b32_e32 v13, 16, v6
	v_mov_b32_e32 v12, v10
	v_pk_mul_f32 v[14:15], v[18:19], v[12:13]
	v_and_b32_e32 v11, 16, v6
	v_add_f32_e32 v6, v15, v22
	v_and_b32_e32 v12, 0xffff0000, v7
	v_add_f32_e32 v14, v14, v6
	v_fma_f32 v15, v21, v13, v20
	v_and_b32_e32 v13, 16, v7
	v_lshlrev_b32_e32 v7, 16, v7
	v_mov_b32_e32 v6, v12
	v_fma_f32 v22, v21, v10, v20
	v_pk_mov_b32 v[10:11], v[6:7], v[10:11] op_sel:[1,0]
	v_fma_f32 v24, v21, v12, v20
	v_pk_mul_f32 v[10:11], v[18:19], v[10:11]
	v_fma_f32 v23, v21, v7, v20
	v_add_f32_e32 v11, v11, v15
	v_add_f32_e32 v15, v10, v11
	v_pk_mul_f32 v[10:11], v[18:19], v[6:7]
	v_and_b32_e32 v7, 16, v8
	v_add_f32_e32 v6, v11, v22
	v_add_f32_e32 v22, v10, v6
	v_and_b32_e32 v6, 0xffff0000, v8
	v_lshlrev_b32_e32 v11, 16, v8
	v_mov_b32_e32 v10, v6
	v_pk_mov_b32 v[12:13], v[10:11], v[12:13] op_sel:[1,0]
	s_nop 0
	v_pk_mul_f32 v[12:13], v[18:19], v[12:13]
	s_nop 0
	v_add_f32_e32 v8, v13, v23
	v_add_f32_e32 v23, v12, v8
	v_pk_mul_f32 v[12:13], v[18:19], v[10:11]
	v_fma_f32 v11, v21, v11, v20
	v_add_f32_e32 v8, v13, v24
	v_add_f32_e32 v10, v12, v8
	v_and_b32_e32 v8, 0xffff0000, v9
	v_lshlrev_b32_e32 v9, 16, v9
	v_fma_f32 v12, v21, v6, v20
	v_pk_mov_b32 v[6:7], v[8:9], v[6:7] op_sel:[1,0]
	v_mov_b32_e32 v57, v8
	v_pk_mul_f32 v[6:7], v[18:19], v[6:7]
	s_nop 0
	v_add_f32_e32 v7, v7, v11
	v_add_f32_e32 v11, v6, v7
	v_pk_mul_f32 v[6:7], v[18:19], v[8:9]
	v_fma_f32 v9, v21, v9, v20
	v_add_f32_e32 v7, v7, v12
	v_add_f32_e32 v12, v6, v7
	s_waitcnt vmcnt(0)
	v_lshlrev_b32_e32 v56, 16, v56
	v_pk_mul_f32 v[6:7], v[56:57], v[18:19]
	s_nop 0
	v_add_f32_e32 v7, v7, v9
	v_add_f32_e32 v9, v6, v7
	v_cvt_pk_bf16_f32 v6, v14, v15
	v_cvt_pk_bf16_f32 v7, v22, v23
	v_cvt_pk_bf16_f32 v8, v10, v11
	v_mad_i32_i24 v10, v17, s58, v16
	v_lshl_add_u32 v10, v10, 1, 0
	v_add_u32_e32 v10, 0x14100, v10
	v_cvt_pk_bf16_f32 v9, v12, v9
	ds_write_b128 v10, v[6:9]
	s_or_b64 exec, exec, s[0:1]
	s_and_saveexec_b64 s[0:1], s[10:11]
	s_cbranch_execnz .LBB0_3404
	s_branch .LBB0_3405

.LBB0_3402:
	s_waitcnt vmcnt(8)
	v_lshrrev_b32_e32 v14, 21, v142
	v_add_u32_e32 v14, v136, v14
	v_and_b32_e32 v14, 0x7ffff800, v14
	s_waitcnt vmcnt(7)
	v_sub_u32_e32 v24, v136, v14
	v_add_u32_sdwa v14, v123, v138 dst_sel:DWORD dst_unused:UNUSED_PAD src0_sel:DWORD src1_sel:BYTE_3
	s_waitcnt vmcnt(5)
	v_lshrrev_b32_e32 v25, 8, v14
	v_lshlrev_b32_e32 v14, 16, v57
	s_waitcnt vmcnt(0)
	v_fma_f32 v26, v21, v14, v20
	v_and_b32_e32 v14, 0xffff0000, v10
	v_lshlrev_b32_e32 v17, 16, v10
	v_mov_b32_e32 v16, v14
	v_pk_mul_f32 v[22:23], v[18:19], v[16:17]
	v_and_b32_e32 v15, 16, v10
	v_add_f32_e32 v10, v23, v26
	v_and_b32_e32 v16, 0xffff0000, v11
	v_add_f32_e32 v22, v22, v10
	v_fma_f32 v23, v21, v17, v20
	v_and_b32_e32 v17, 16, v11
	v_lshlrev_b32_e32 v11, 16, v11
	v_mov_b32_e32 v10, v16
	v_fma_f32 v26, v21, v14, v20
	v_pk_mov_b32 v[14:15], v[10:11], v[14:15] op_sel:[1,0]
	v_fma_f32 v28, v21, v16, v20
	v_pk_mul_f32 v[14:15], v[18:19], v[14:15]
	v_fma_f32 v27, v21, v11, v20
	v_add_f32_e32 v15, v15, v23
	v_add_f32_e32 v23, v14, v15
	v_pk_mul_f32 v[14:15], v[18:19], v[10:11]
	v_and_b32_e32 v11, 16, v12
	v_add_f32_e32 v10, v15, v26
	v_add_f32_e32 v26, v14, v10
	v_and_b32_e32 v10, 0xffff0000, v12
	v_lshlrev_b32_e32 v15, 16, v12
	v_mov_b32_e32 v14, v10
	v_pk_mov_b32 v[16:17], v[14:15], v[16:17] op_sel:[1,0]
	s_nop 0
	v_pk_mul_f32 v[16:17], v[18:19], v[16:17]
	s_nop 0
	v_add_f32_e32 v12, v17, v27
	v_add_f32_e32 v27, v16, v12
	v_pk_mul_f32 v[16:17], v[18:19], v[14:15]
	v_fma_f32 v15, v21, v15, v20
	v_add_f32_e32 v12, v17, v28
	v_add_f32_e32 v14, v16, v12
	v_and_b32_e32 v12, 0xffff0000, v13
	v_lshlrev_b32_e32 v13, 16, v13
	v_fma_f32 v16, v21, v10, v20
	v_pk_mov_b32 v[10:11], v[12:13], v[10:11] op_sel:[1,0]
	v_mov_b32_e32 v59, v12
	v_pk_mul_f32 v[10:11], v[18:19], v[10:11]
	s_nop 0
	v_add_f32_e32 v11, v11, v15
	v_add_f32_e32 v15, v10, v11
	v_pk_mul_f32 v[10:11], v[18:19], v[12:13]
	v_fma_f32 v13, v21, v13, v20
	v_add_f32_e32 v11, v11, v16
	v_add_f32_e32 v16, v10, v11
	s_waitcnt vmcnt(0)
	v_lshlrev_b32_e32 v58, 16, v58
	v_pk_mul_f32 v[10:11], v[58:59], v[18:19]
	s_nop 0
	v_add_f32_e32 v11, v11, v13
	v_add_f32_e32 v13, v10, v11
	v_cvt_pk_bf16_f32 v10, v22, v23
	v_cvt_pk_bf16_f32 v11, v26, v27
	v_cvt_pk_bf16_f32 v12, v14, v15
	v_mad_i32_i24 v14, v25, s58, v24
	v_lshl_add_u32 v14, v14, 1, 0
	v_add_u32_e32 v14, 0x14100, v14
	v_cvt_pk_bf16_f32 v13, v16, v13
	ds_write_b128 v14, v[10:13]
	s_or_b64 exec, exec, s[0:1]
	s_and_saveexec_b64 s[0:1], s[12:13]
	s_cbranch_execnz .LBB0_3398

.LBB0_3404:
	s_waitcnt vmcnt(8)
	v_lshrrev_b32_e32 v6, 21, v146
	v_add_u32_e32 v6, v143, v6
	v_and_b32_e32 v6, 0x7ffff800, v6
	v_sub_u32_e32 v12, v143, v6
	v_add_u32_sdwa v6, v140, v144 dst_sel:DWORD dst_unused:UNUSED_PAD src0_sel:DWORD src1_sel:BYTE_3
	v_lshrrev_b32_e32 v13, 8, v6
	v_lshlrev_b32_e32 v6, 16, v47
	s_waitcnt vmcnt(0)
	v_fma_f32 v14, v21, v6, v20
	v_and_b32_e32 v6, 0xffff0000, v2
	v_lshlrev_b32_e32 v9, 16, v2
	v_mov_b32_e32 v8, v6
	v_pk_mul_f32 v[10:11], v[18:19], v[8:9]
	v_and_b32_e32 v7, 16, v2
	v_add_f32_e32 v2, v11, v14
	v_and_b32_e32 v8, 0xffff0000, v3
	v_add_f32_e32 v10, v10, v2
	v_fma_f32 v11, v21, v9, v20
	v_and_b32_e32 v9, 16, v3
	v_lshlrev_b32_e32 v3, 16, v3
	v_mov_b32_e32 v2, v8
	v_fma_f32 v14, v21, v6, v20
	v_pk_mov_b32 v[6:7], v[2:3], v[6:7] op_sel:[1,0]
	v_fma_f32 v16, v21, v8, v20
	v_pk_mul_f32 v[6:7], v[18:19], v[6:7]
	v_fma_f32 v15, v21, v3, v20
	v_add_f32_e32 v7, v7, v11
	v_add_f32_e32 v11, v6, v7
	v_pk_mul_f32 v[6:7], v[18:19], v[2:3]
	v_and_b32_e32 v3, 16, v4
	v_add_f32_e32 v2, v7, v14
	v_add_f32_e32 v14, v6, v2
	v_and_b32_e32 v2, 0xffff0000, v4
	v_lshlrev_b32_e32 v7, 16, v4
	v_mov_b32_e32 v6, v2
	v_pk_mov_b32 v[8:9], v[6:7], v[8:9] op_sel:[1,0]
	s_nop 0
	v_pk_mul_f32 v[8:9], v[18:19], v[8:9]
	s_nop 0
	v_add_f32_e32 v4, v9, v15
	v_add_f32_e32 v15, v8, v4
	v_pk_mul_f32 v[8:9], v[18:19], v[6:7]
	v_fma_f32 v7, v21, v7, v20
	v_add_f32_e32 v4, v9, v16
	v_add_f32_e32 v6, v8, v4
	v_and_b32_e32 v4, 0xffff0000, v5
	v_lshlrev_b32_e32 v5, 16, v5
	v_fma_f32 v8, v21, v2, v20
	v_pk_mov_b32 v[2:3], v[4:5], v[2:3] op_sel:[1,0]
	v_mov_b32_e32 v55, v4
	v_pk_mul_f32 v[2:3], v[18:19], v[2:3]
	v_fmac_f32_e32 v20, v21, v5
	v_add_f32_e32 v3, v3, v7
	v_add_f32_e32 v7, v2, v3
	v_pk_mul_f32 v[2:3], v[18:19], v[4:5]
	s_nop 0
	v_add_f32_e32 v3, v3, v8
	v_add_f32_e32 v8, v2, v3
	s_waitcnt vmcnt(0)
	v_lshlrev_b32_e32 v54, 16, v54
	v_pk_mul_f32 v[2:3], v[54:55], v[18:19]
	s_nop 0
	v_add_f32_e32 v3, v3, v20
	v_add_f32_e32 v5, v2, v3
	v_cvt_pk_bf16_f32 v2, v10, v11
	v_cvt_pk_bf16_f32 v3, v14, v15
	v_cvt_pk_bf16_f32 v4, v6, v7
	v_mad_i32_i24 v6, v13, s58, v12
	v_lshl_add_u32 v6, v6, 1, 0
	v_add_u32_e32 v6, 0x14100, v6
	v_cvt_pk_bf16_f32 v5, v8, v5
	ds_write_b128 v6, v[2:5]

.LBB0_3420:
	s_or_b64 exec, exec, s[28:29]
	v_cmp_gt_i32_e64 s[0:1], s49, v119
	s_and_saveexec_b64 s[28:29], s[0:1]
	s_cbranch_execz .LBB0_3422
	global_load_ushort v124, v[2:3], off offset:16

.LBB0_3426:
	s_or_b64 exec, exec, s[28:29]
	v_cmp_gt_i32_e64 s[0:1], s49, v78
	s_and_saveexec_b64 s[28:29], s[0:1]
	s_cbranch_execz .LBB0_3428
	global_load_ushort v122, v[2:3], off offset:16

.LBB0_3432:
	s_or_b64 exec, exec, s[28:29]
	v_cmp_gt_i32_e64 s[0:1], s49, v94
	s_and_saveexec_b64 s[28:29], s[0:1]
	s_cbranch_execz .LBB0_3434
	global_load_ushort v120, v[2:3], off offset:16

.LBB0_3438:
	s_or_b64 exec, exec, s[16:17]
	v_cmp_gt_i32_e64 s[0:1], s49, v95
	s_and_saveexec_b64 s[16:17], s[0:1]
	s_cbranch_execz .LBB0_3440
	global_load_ushort v118, v[2:3], off offset:16

.LBB0_3461:
	s_or_b64 exec, exec, s[0:1]
	s_waitcnt lgkmcnt(0)
	s_barrier
	global_load_dword v3, v132, s[22:23]
	global_load_dword v2, v133, s[22:23]
	global_load_dword v5, v131, s[22:23]
	global_load_dword v4, v131, s[24:25]
	s_and_saveexec_b64 s[0:1], vcc
	s_cbranch_execz .LBB0_3467
	s_waitcnt vmcnt(4)
	v_lshlrev_b32_e32 v6, 16, v157
	s_waitcnt vmcnt(0)
	v_fma_f32 v13, v5, v6, v4
	v_and_b32_e32 v6, 0xffff0000, v90
	v_lshlrev_b32_e32 v9, 16, v90
	v_mov_b32_e32 v8, v6
	v_pk_mul_f32 v[10:11], v[2:3], v[8:9]
	v_and_b32_e32 v7, 16, v90
	v_add_f32_e32 v8, v11, v13
	v_add_f32_e32 v13, v10, v8
	v_and_b32_e32 v8, 0xffff0000, v91
	v_lshlrev_b32_e32 v11, 16, v91
	v_mov_b32_e32 v10, v8
	v_fma_f32 v15, v5, v6, v4
	v_pk_mov_b32 v[6:7], v[10:11], v[6:7] op_sel:[1,0]
	v_fma_f32 v14, v5, v9, v4
	v_pk_mul_f32 v[6:7], v[2:3], v[6:7]
	v_and_b32_e32 v9, 16, v91
	v_add_f32_e32 v7, v7, v14
	v_add_f32_e32 v14, v6, v7
	v_pk_mul_f32 v[6:7], v[2:3], v[10:11]
	v_fma_f32 v16, v5, v11, v4
	v_add_f32_e32 v7, v7, v15
	v_add_f32_e32 v15, v6, v7
	v_and_b32_e32 v6, 0xffff0000, v92
	v_lshlrev_b32_e32 v11, 16, v92
	v_mov_b32_e32 v10, v6
	v_fma_f32 v17, v5, v8, v4
	v_pk_mov_b32 v[8:9], v[10:11], v[8:9] op_sel:[1,0]
	v_and_b32_e32 v7, 16, v92
	v_pk_mul_f32 v[8:9], v[2:3], v[8:9]
	v_lshrrev_b32_e32 v12, 8, v125
	v_add_f32_e32 v9, v9, v16
	v_add_f32_e32 v16, v8, v9
	v_pk_mul_f32 v[8:9], v[2:3], v[10:11]
	v_fma_f32 v11, v5, v11, v4
	v_add_f32_e32 v9, v9, v17
	v_add_f32_e32 v10, v8, v9
	v_and_b32_e32 v8, 0xffff0000, v93
	v_lshlrev_b32_e32 v9, 16, v93
	v_fma_f32 v17, v5, v6, v4
	v_pk_mov_b32 v[6:7], v[8:9], v[6:7] op_sel:[1,0]
	v_mov_b32_e32 v125, v8
	v_pk_mul_f32 v[6:7], v[2:3], v[6:7]
	s_nop 0
	v_add_f32_e32 v7, v7, v11
	v_add_f32_e32 v11, v6, v7
	v_pk_mul_f32 v[6:7], v[2:3], v[8:9]
	v_fma_f32 v9, v5, v9, v4
	v_add_f32_e32 v7, v7, v17
	v_add_f32_e32 v17, v6, v7
	s_waitcnt vmcnt(0)
	v_lshlrev_b32_e32 v124, 16, v124
	v_pk_mul_f32 v[6:7], v[124:125], v[2:3]
	s_nop 0
	v_add_f32_e32 v7, v7, v9
	v_add_f32_e32 v9, v6, v7
	v_cvt_pk_bf16_f32 v6, v13, v14
	v_cvt_pk_bf16_f32 v7, v15, v16
	v_cvt_pk_bf16_f32 v8, v10, v11
	v_mad_i32_i24 v10, v12, s58, v119
	v_lshl_add_u32 v10, v10, 1, 0
	v_add_u32_e32 v10, 0x14100, v10
	v_cvt_pk_bf16_f32 v9, v17, v9
	ds_write_b128 v10, v[6:9]
	s_or_b64 exec, exec, s[0:1]
	s_and_saveexec_b64 s[0:1], s[14:15]
	s_cbranch_execnz .LBB0_3468

.LBB0_3464:
	v_lshrrev_b32_e32 v6, 21, v145
	v_add_u32_e32 v6, v139, v6
	v_and_b32_e32 v6, 0x7ffff800, v6
	v_sub_u32_e32 v12, v139, v6
	v_add_u32_sdwa v6, v137, v141 dst_sel:DWORD dst_unused:UNUSED_PAD src0_sel:DWORD src1_sel:BYTE_3
	v_lshrrev_b32_e32 v13, 8, v6
	s_waitcnt vmcnt(4)
	v_lshlrev_b32_e32 v6, 16, v155
	s_waitcnt vmcnt(0)
	v_fma_f32 v14, v5, v6, v4
	v_and_b32_e32 v6, 0xffff0000, v76
	v_lshlrev_b32_e32 v9, 16, v76
	v_mov_b32_e32 v8, v6
	v_pk_mul_f32 v[10:11], v[2:3], v[8:9]
	v_and_b32_e32 v7, 16, v76
	v_add_f32_e32 v8, v11, v14
	v_add_f32_e32 v14, v10, v8
	v_and_b32_e32 v8, 0xffff0000, v77
	v_lshlrev_b32_e32 v11, 16, v77
	v_mov_b32_e32 v10, v8
	v_fma_f32 v16, v5, v6, v4
	v_pk_mov_b32 v[6:7], v[10:11], v[6:7] op_sel:[1,0]
	v_fma_f32 v15, v5, v9, v4
	v_pk_mul_f32 v[6:7], v[2:3], v[6:7]
	v_and_b32_e32 v9, 16, v77
	v_add_f32_e32 v7, v7, v15
	v_add_f32_e32 v15, v6, v7
	v_pk_mul_f32 v[6:7], v[2:3], v[10:11]
	v_fma_f32 v17, v5, v11, v4
	v_add_f32_e32 v7, v7, v16
	v_add_f32_e32 v16, v6, v7
	v_and_b32_e32 v6, 0xffff0000, v78
	v_lshlrev_b32_e32 v11, 16, v78
	v_mov_b32_e32 v10, v6
	v_fma_f32 v18, v5, v8, v4
	v_pk_mov_b32 v[8:9], v[10:11], v[8:9] op_sel:[1,0]
	v_and_b32_e32 v7, 16, v78
	v_pk_mul_f32 v[8:9], v[2:3], v[8:9]
	s_nop 0
	v_add_f32_e32 v9, v9, v17
	v_add_f32_e32 v17, v8, v9
	v_pk_mul_f32 v[8:9], v[2:3], v[10:11]
	v_fma_f32 v11, v5, v11, v4
	v_add_f32_e32 v9, v9, v18
	v_add_f32_e32 v10, v8, v9
	v_and_b32_e32 v8, 0xffff0000, v79
	v_lshlrev_b32_e32 v9, 16, v79
	v_fma_f32 v18, v5, v6, v4
	v_pk_mov_b32 v[6:7], v[8:9], v[6:7] op_sel:[1,0]
	v_mov_b32_e32 v121, v8
	v_pk_mul_f32 v[6:7], v[2:3], v[6:7]
	s_nop 0
	v_add_f32_e32 v7, v7, v11
	v_add_f32_e32 v11, v6, v7
	v_pk_mul_f32 v[6:7], v[2:3], v[8:9]
	v_fma_f32 v9, v5, v9, v4
	v_add_f32_e32 v7, v7, v18
	v_add_f32_e32 v18, v6, v7
	s_waitcnt vmcnt(0)
	v_lshlrev_b32_e32 v120, 16, v120
	v_pk_mul_f32 v[6:7], v[120:121], v[2:3]
	s_nop 0
	v_add_f32_e32 v7, v7, v9
	v_add_f32_e32 v9, v6, v7
	v_cvt_pk_bf16_f32 v6, v14, v15
	v_cvt_pk_bf16_f32 v7, v16, v17
	v_cvt_pk_bf16_f32 v8, v10, v11
	v_mad_i32_i24 v10, v13, s58, v12
	v_lshl_add_u32 v10, v10, 1, 0
	v_add_u32_e32 v10, 0x14100, v10
	v_cvt_pk_bf16_f32 v9, v18, v9
	ds_write_b128 v10, v[6:9]
	s_or_b64 exec, exec, s[0:1]
	s_and_saveexec_b64 s[0:1], s[10:11]
	s_cbranch_execnz .LBB0_3470
	s_branch .LBB0_3471

.LBB0_3468:
	v_lshrrev_b32_e32 v6, 21, v142
	v_add_u32_e32 v6, v136, v6
	v_and_b32_e32 v6, 0x7ffff800, v6
	v_sub_u32_e32 v12, v136, v6
	v_add_u32_sdwa v6, v123, v138 dst_sel:DWORD dst_unused:UNUSED_PAD src0_sel:DWORD src1_sel:BYTE_3
	v_lshrrev_b32_e32 v13, 8, v6
	s_waitcnt vmcnt(4)
	v_lshlrev_b32_e32 v6, 16, v156
	s_waitcnt vmcnt(0)
	v_fma_f32 v14, v5, v6, v4
	v_and_b32_e32 v6, 0xffff0000, v80
	v_lshlrev_b32_e32 v9, 16, v80
	v_mov_b32_e32 v8, v6
	v_pk_mul_f32 v[10:11], v[2:3], v[8:9]
	v_and_b32_e32 v7, 16, v80
	v_add_f32_e32 v8, v11, v14
	v_add_f32_e32 v14, v10, v8
	v_and_b32_e32 v8, 0xffff0000, v81
	v_lshlrev_b32_e32 v11, 16, v81
	v_mov_b32_e32 v10, v8
	v_fma_f32 v16, v5, v6, v4
	v_pk_mov_b32 v[6:7], v[10:11], v[6:7] op_sel:[1,0]
	v_fma_f32 v15, v5, v9, v4
	v_pk_mul_f32 v[6:7], v[2:3], v[6:7]
	v_and_b32_e32 v9, 16, v81
	v_add_f32_e32 v7, v7, v15
	v_add_f32_e32 v15, v6, v7
	v_pk_mul_f32 v[6:7], v[2:3], v[10:11]
	v_fma_f32 v17, v5, v11, v4
	v_add_f32_e32 v7, v7, v16
	v_add_f32_e32 v16, v6, v7
	v_and_b32_e32 v6, 0xffff0000, v82
	v_lshlrev_b32_e32 v11, 16, v82
	v_mov_b32_e32 v10, v6
	v_fma_f32 v18, v5, v8, v4
	v_pk_mov_b32 v[8:9], v[10:11], v[8:9] op_sel:[1,0]
	v_and_b32_e32 v7, 16, v82
	v_pk_mul_f32 v[8:9], v[2:3], v[8:9]
	s_nop 0
	v_add_f32_e32 v9, v9, v17
	v_add_f32_e32 v17, v8, v9
	v_pk_mul_f32 v[8:9], v[2:3], v[10:11]
	v_fma_f32 v11, v5, v11, v4
	v_add_f32_e32 v9, v9, v18
	v_add_f32_e32 v10, v8, v9
	v_and_b32_e32 v8, 0xffff0000, v83
	v_lshlrev_b32_e32 v9, 16, v83
	v_fma_f32 v18, v5, v6, v4
	v_pk_mov_b32 v[6:7], v[8:9], v[6:7] op_sel:[1,0]
	v_mov_b32_e32 v123, v8
	v_pk_mul_f32 v[6:7], v[2:3], v[6:7]
	s_nop 0
	v_add_f32_e32 v7, v7, v11
	v_add_f32_e32 v11, v6, v7
	v_pk_mul_f32 v[6:7], v[2:3], v[8:9]
	v_fma_f32 v9, v5, v9, v4
	v_add_f32_e32 v7, v7, v18
	v_add_f32_e32 v18, v6, v7
	s_waitcnt vmcnt(0)
	v_lshlrev_b32_e32 v122, 16, v122
	v_pk_mul_f32 v[6:7], v[122:123], v[2:3]
	s_nop 0
	v_add_f32_e32 v7, v7, v9
	v_add_f32_e32 v9, v6, v7
	v_cvt_pk_bf16_f32 v6, v14, v15
	v_cvt_pk_bf16_f32 v7, v16, v17
	v_cvt_pk_bf16_f32 v8, v10, v11
	v_mad_i32_i24 v10, v13, s58, v12
	v_lshl_add_u32 v10, v10, 1, 0
	v_add_u32_e32 v10, 0x14100, v10
	v_cvt_pk_bf16_f32 v9, v18, v9
	ds_write_b128 v10, v[6:9]
	s_or_b64 exec, exec, s[0:1]
	s_and_saveexec_b64 s[0:1], s[12:13]
	s_cbranch_execnz .LBB0_3464

.LBB0_3470:
	v_lshrrev_b32_e32 v6, 21, v146
	v_add_u32_e32 v6, v143, v6
	v_and_b32_e32 v6, 0x7ffff800, v6
	v_sub_u32_e32 v12, v143, v6
	v_add_u32_sdwa v6, v140, v144 dst_sel:DWORD dst_unused:UNUSED_PAD src0_sel:DWORD src1_sel:BYTE_3
	v_lshrrev_b32_e32 v13, 8, v6
	s_waitcnt vmcnt(4)
	v_lshlrev_b32_e32 v6, 16, v154
	s_waitcnt vmcnt(0)
	v_fma_f32 v14, v5, v6, v4
	v_and_b32_e32 v6, 0xffff0000, v66
	v_lshlrev_b32_e32 v9, 16, v66
	v_mov_b32_e32 v8, v6
	v_pk_mul_f32 v[10:11], v[2:3], v[8:9]
	v_and_b32_e32 v7, 16, v66
	v_add_f32_e32 v8, v11, v14
	v_add_f32_e32 v14, v10, v8
	v_and_b32_e32 v8, 0xffff0000, v67
	v_lshlrev_b32_e32 v11, 16, v67
	v_mov_b32_e32 v10, v8
	v_fma_f32 v16, v5, v6, v4
	v_pk_mov_b32 v[6:7], v[10:11], v[6:7] op_sel:[1,0]
	v_fma_f32 v15, v5, v9, v4
	v_pk_mul_f32 v[6:7], v[2:3], v[6:7]
	v_and_b32_e32 v9, 16, v67
	v_add_f32_e32 v7, v7, v15
	v_add_f32_e32 v15, v6, v7
	v_pk_mul_f32 v[6:7], v[2:3], v[10:11]
	v_fma_f32 v17, v5, v11, v4
	v_add_f32_e32 v7, v7, v16
	v_add_f32_e32 v16, v6, v7
	v_and_b32_e32 v6, 0xffff0000, v68
	v_lshlrev_b32_e32 v11, 16, v68
	v_mov_b32_e32 v10, v6
	v_fma_f32 v18, v5, v8, v4
	v_pk_mov_b32 v[8:9], v[10:11], v[8:9] op_sel:[1,0]
	v_and_b32_e32 v7, 16, v68
	v_pk_mul_f32 v[8:9], v[2:3], v[8:9]
	s_nop 0
	v_add_f32_e32 v9, v9, v17
	v_add_f32_e32 v17, v8, v9
	v_pk_mul_f32 v[8:9], v[2:3], v[10:11]
	v_fma_f32 v11, v5, v11, v4
	v_add_f32_e32 v9, v9, v18
	v_add_f32_e32 v10, v8, v9
	v_and_b32_e32 v8, 0xffff0000, v69
	v_lshlrev_b32_e32 v9, 16, v69
	v_fma_f32 v18, v5, v6, v4
	v_pk_mov_b32 v[6:7], v[8:9], v[6:7] op_sel:[1,0]
	v_mov_b32_e32 v119, v8
	v_pk_mul_f32 v[6:7], v[2:3], v[6:7]
	v_fmac_f32_e32 v4, v5, v9
	v_add_f32_e32 v7, v7, v11
	v_add_f32_e32 v11, v6, v7
	v_pk_mul_f32 v[6:7], v[2:3], v[8:9]
	s_waitcnt vmcnt(0)
	v_lshlrev_b32_e32 v118, 16, v118
	v_pk_mul_f32 v[2:3], v[118:119], v[2:3]
	v_add_f32_e32 v7, v7, v18
	v_add_f32_e32 v3, v3, v4
	v_add_f32_e32 v6, v6, v7
	v_add_f32_e32 v5, v2, v3
	v_cvt_pk_bf16_f32 v2, v14, v15
	v_cvt_pk_bf16_f32 v3, v16, v17
	v_cvt_pk_bf16_f32 v4, v10, v11
	v_cvt_pk_bf16_f32 v5, v6, v5
	v_mad_i32_i24 v6, v13, s58, v12
	v_lshl_add_u32 v6, v6, 1, 0
	v_add_u32_e32 v6, 0x14100, v6
	ds_write_b128 v6, v[2:5]
